# per-piece counted vmcnt waits in the three straight-line residual epilogues (each piece waits only for its own loads); otherwise v048
# baseline (speedup 1.0000x reference)
.Lrfast_ffo:
	v_lshlrev_b32_e32 v134, 12, v180
	v_lshl_add_u32 v134, v178, 1, v134
	v_add_u32_e32 v135, 0x80000, v134
	v_lshl_add_u32 v138, v191, 4, v180
	v_lshlrev_b32_e32 v138, 3, v138
	s_add_u32 s6, s18, 0x10000
	s_addc_u32 s7, s19, 0
	s_add_u32 s8, s18, 0x20000
	s_addc_u32 s9, s19, 0
	s_add_u32 s10, s18, 0x30000
	s_addc_u32 s11, s19, 0
	v_lshlrev_b32_e32 v136, 3, v4
	v_add_u32_e32 v136, 0x20000, v136
	v_lshlrev_b32_e32 v137, 2, v2
	v_add_u32_e32 v137, 0x20800, v137
	global_load_dwordx4 v[204:207], v134, s[18:19]
	global_load_dwordx4 v[208:211], v134, s[6:7]
	global_load_dwordx4 v[212:215], v134, s[8:9]
	global_load_dwordx4 v[216:219], v134, s[10:11]
	global_load_dwordx4 v[222:225], v134, s[18:19] offset:256
	global_load_dwordx4 v[182:185], v134, s[6:7] offset:256
	global_load_dwordx4 v[166:169], v134, s[8:9] offset:256
	global_load_dwordx4 v[170:173], v134, s[10:11] offset:256
	ds_read2_b64 v[142:145], v136 offset0:0 offset1:16
	ds_read2_b64 v[146:149], v136 offset0:32 offset1:48
	ds_read_b128 v[150:153], v137
	ds_read_b128 v[154:157], v137 offset:16
	ds_read_b128 v[158:161], v137 offset:1024
	ds_read_b128 v[162:165], v137 offset:1040
	v_cmp_lt_i32_e32 vcc, v234, v230
	s_nop 1
	v_cndmask_b32_e32 v201, v228, v234, vcc
	v_cmp_lt_i32_e32 vcc, v195, v230
	s_nop 1
	v_cndmask_b32_e32 v203, v228, v195, vcc
	v_lshlrev_b32_e32 v201, 2, v201
	v_lshlrev_b32_e32 v203, 2, v203
	s_waitcnt lgkmcnt(0)
	v_mul_f32_e32 v142, 0x3a000000, v142
	v_mul_f32_e32 v174, v142, v142
	v_fma_f32 v174, v143, s72, -v174
	v_add_f32_e32 v174, 0x3727c5ac, v174
	v_mul_f32_e32 v144, 0x3a000000, v144
	v_mul_f32_e32 v175, v144, v144
	v_fma_f32 v175, v145, s72, -v175
	v_add_f32_e32 v175, 0x3727c5ac, v175
	v_mul_f32_e32 v146, 0x3a000000, v146
	v_mul_f32_e32 v176, v146, v146
	v_fma_f32 v176, v147, s72, -v176
	v_add_f32_e32 v176, 0x3727c5ac, v176
	v_mul_f32_e32 v148, 0x3a000000, v148
	v_mul_f32_e32 v177, v148, v148
	v_fma_f32 v177, v149, s72, -v177
	v_add_f32_e32 v177, 0x3727c5ac, v177
	v_rsq_f32_e32 v143, v174
	v_rsq_f32_e32 v145, v175
	v_rsq_f32_e32 v147, v176
	v_rsq_f32_e32 v149, v177
	s_nop 0
	s_waitcnt vmcnt(7)
	v_lshlrev_b32_e32 v174, 16, v204
	v_and_b32_e32 v175, 0xffff0000, v204
	v_lshlrev_b32_e32 v176, 16, v205
	v_and_b32_e32 v177, 0xffff0000, v205
	v_lshlrev_b32_e32 v178, 16, v206
	v_and_b32_e32 v179, 0xffff0000, v206
	v_lshlrev_b32_e32 v180, 16, v207
	v_and_b32_e32 v181, 0xffff0000, v207
	v_pk_add_f32 v[174:175], v[174:175], v[142:143] op_sel_hi:[1,0] neg_lo:[0,1] neg_hi:[0,1]
	v_pk_add_f32 v[176:177], v[176:177], v[142:143] op_sel_hi:[1,0] neg_lo:[0,1] neg_hi:[0,1]
	v_pk_add_f32 v[178:179], v[178:179], v[142:143] op_sel_hi:[1,0] neg_lo:[0,1] neg_hi:[0,1]
	v_pk_add_f32 v[180:181], v[180:181], v[142:143] op_sel_hi:[1,0] neg_lo:[0,1] neg_hi:[0,1]
	v_pk_mul_f32 v[174:175], v[142:143], v[174:175] op_sel:[1,0] op_sel_hi:[1,1]
	v_pk_mul_f32 v[176:177], v[142:143], v[176:177] op_sel:[1,0] op_sel_hi:[1,1]
	v_pk_mul_f32 v[178:179], v[142:143], v[178:179] op_sel:[1,0] op_sel_hi:[1,1]
	v_pk_mul_f32 v[180:181], v[142:143], v[180:181] op_sel:[1,0] op_sel_hi:[1,1]
	v_pk_fma_f32 v[174:175], v[150:151], v[174:175], v[158:159]
	v_pk_fma_f32 v[176:177], v[152:153], v[176:177], v[160:161]
	v_pk_fma_f32 v[178:179], v[154:155], v[178:179], v[162:163]
	v_pk_fma_f32 v[180:181], v[156:157], v[180:181], v[164:165]
	v_pk_mul_f32 v[174:175], v[174:175], s[76:77] op_sel_hi:[1,0]
	v_pk_mul_f32 v[176:177], v[176:177], s[76:77] op_sel_hi:[1,0]
	v_pk_mul_f32 v[178:179], v[178:179], s[76:77] op_sel_hi:[1,0]
	v_pk_mul_f32 v[180:181], v[180:181], s[76:77] op_sel_hi:[1,0]
	v_pk_fma_f32 v[126:127], v[126:127], 0.5, v[174:175] op_sel_hi:[1,0,1]
	v_pk_fma_f32 v[128:129], v[128:129], 0.5, v[176:177] op_sel_hi:[1,0,1]
	v_pk_fma_f32 v[130:131], v[130:131], 0.5, v[178:179] op_sel_hi:[1,0,1]
	v_pk_fma_f32 v[132:133], v[132:133], 0.5, v[180:181] op_sel_hi:[1,0,1]
	v_pk_add_f32 v[174:175], v[126:127], v[130:131]
	v_pk_add_f32 v[176:177], v[128:129], v[132:133]
	v_pk_mul_f32 v[178:179], v[126:127], v[126:127]
	v_pk_mul_f32 v[180:181], v[128:129], v[128:129]
	v_pk_fma_f32 v[178:179], v[130:131], v[130:131], v[178:179]
	v_pk_fma_f32 v[180:181], v[132:133], v[132:133], v[180:181]
	v_pk_add_f32 v[174:175], v[174:175], v[176:177]
	v_pk_add_f32 v[178:179], v[178:179], v[180:181]
	v_cvt_pk_bf16_f32 v204, v126, v127
	v_cvt_pk_bf16_f32 v205, v128, v129
	v_cvt_pk_bf16_f32 v206, v130, v131
	v_cvt_pk_bf16_f32 v207, v132, v133
	v_add_f32_e32 v2, v174, v175
	v_add_f32_e32 v140, v178, v179
	s_waitcnt vmcnt(6)
	v_lshlrev_b32_e32 v174, 16, v208
	v_and_b32_e32 v175, 0xffff0000, v208
	v_lshlrev_b32_e32 v176, 16, v209
	v_and_b32_e32 v177, 0xffff0000, v209
	v_lshlrev_b32_e32 v178, 16, v210
	v_and_b32_e32 v179, 0xffff0000, v210
	v_lshlrev_b32_e32 v180, 16, v211
	v_and_b32_e32 v181, 0xffff0000, v211
	v_pk_add_f32 v[174:175], v[174:175], v[144:145] op_sel_hi:[1,0] neg_lo:[0,1] neg_hi:[0,1]
	v_pk_add_f32 v[176:177], v[176:177], v[144:145] op_sel_hi:[1,0] neg_lo:[0,1] neg_hi:[0,1]
	v_pk_add_f32 v[178:179], v[178:179], v[144:145] op_sel_hi:[1,0] neg_lo:[0,1] neg_hi:[0,1]
	v_pk_add_f32 v[180:181], v[180:181], v[144:145] op_sel_hi:[1,0] neg_lo:[0,1] neg_hi:[0,1]
	v_pk_mul_f32 v[174:175], v[144:145], v[174:175] op_sel:[1,0] op_sel_hi:[1,1]
	v_pk_mul_f32 v[176:177], v[144:145], v[176:177] op_sel:[1,0] op_sel_hi:[1,1]
	v_pk_mul_f32 v[178:179], v[144:145], v[178:179] op_sel:[1,0] op_sel_hi:[1,1]
	v_pk_mul_f32 v[180:181], v[144:145], v[180:181] op_sel:[1,0] op_sel_hi:[1,1]
	v_pk_fma_f32 v[174:175], v[150:151], v[174:175], v[158:159]
	v_pk_fma_f32 v[176:177], v[152:153], v[176:177], v[160:161]
	v_pk_fma_f32 v[178:179], v[154:155], v[178:179], v[162:163]
	v_pk_fma_f32 v[180:181], v[156:157], v[180:181], v[164:165]
	v_pk_mul_f32 v[174:175], v[174:175], s[76:77] op_sel_hi:[1,0]
	v_pk_mul_f32 v[176:177], v[176:177], s[76:77] op_sel_hi:[1,0]
	v_pk_mul_f32 v[178:179], v[178:179], s[76:77] op_sel_hi:[1,0]
	v_pk_mul_f32 v[180:181], v[180:181], s[76:77] op_sel_hi:[1,0]
	v_pk_fma_f32 v[118:119], v[118:119], 0.5, v[174:175] op_sel_hi:[1,0,1]
	v_pk_fma_f32 v[120:121], v[120:121], 0.5, v[176:177] op_sel_hi:[1,0,1]
	v_pk_fma_f32 v[122:123], v[122:123], 0.5, v[178:179] op_sel_hi:[1,0,1]
	v_pk_fma_f32 v[124:125], v[124:125], 0.5, v[180:181] op_sel_hi:[1,0,1]
	v_pk_add_f32 v[174:175], v[118:119], v[122:123]
	v_pk_add_f32 v[176:177], v[120:121], v[124:125]
	v_pk_mul_f32 v[178:179], v[118:119], v[118:119]
	v_pk_mul_f32 v[180:181], v[120:121], v[120:121]
	v_pk_fma_f32 v[178:179], v[122:123], v[122:123], v[178:179]
	v_pk_fma_f32 v[180:181], v[124:125], v[124:125], v[180:181]
	v_pk_add_f32 v[174:175], v[174:175], v[176:177]
	v_pk_add_f32 v[178:179], v[178:179], v[180:181]
	v_cvt_pk_bf16_f32 v208, v118, v119
	v_cvt_pk_bf16_f32 v209, v120, v121
	v_cvt_pk_bf16_f32 v210, v122, v123
	v_cvt_pk_bf16_f32 v211, v124, v125
	v_add_f32_e32 v4, v174, v175
	v_add_f32_e32 v186, v178, v179
	s_waitcnt vmcnt(5)
	v_lshlrev_b32_e32 v174, 16, v212
	v_and_b32_e32 v175, 0xffff0000, v212
	v_lshlrev_b32_e32 v176, 16, v213
	v_and_b32_e32 v177, 0xffff0000, v213
	v_lshlrev_b32_e32 v178, 16, v214
	v_and_b32_e32 v179, 0xffff0000, v214
	v_lshlrev_b32_e32 v180, 16, v215
	v_and_b32_e32 v181, 0xffff0000, v215
	v_pk_add_f32 v[174:175], v[174:175], v[146:147] op_sel_hi:[1,0] neg_lo:[0,1] neg_hi:[0,1]
	v_pk_add_f32 v[176:177], v[176:177], v[146:147] op_sel_hi:[1,0] neg_lo:[0,1] neg_hi:[0,1]
	v_pk_add_f32 v[178:179], v[178:179], v[146:147] op_sel_hi:[1,0] neg_lo:[0,1] neg_hi:[0,1]
	v_pk_add_f32 v[180:181], v[180:181], v[146:147] op_sel_hi:[1,0] neg_lo:[0,1] neg_hi:[0,1]
	v_pk_mul_f32 v[174:175], v[146:147], v[174:175] op_sel:[1,0] op_sel_hi:[1,1]
	v_pk_mul_f32 v[176:177], v[146:147], v[176:177] op_sel:[1,0] op_sel_hi:[1,1]
	v_pk_mul_f32 v[178:179], v[146:147], v[178:179] op_sel:[1,0] op_sel_hi:[1,1]
	v_pk_mul_f32 v[180:181], v[146:147], v[180:181] op_sel:[1,0] op_sel_hi:[1,1]
	v_pk_fma_f32 v[174:175], v[150:151], v[174:175], v[158:159]
	v_pk_fma_f32 v[176:177], v[152:153], v[176:177], v[160:161]
	v_pk_fma_f32 v[178:179], v[154:155], v[178:179], v[162:163]
	v_pk_fma_f32 v[180:181], v[156:157], v[180:181], v[164:165]
	v_pk_mul_f32 v[174:175], v[174:175], s[76:77] op_sel_hi:[1,0]
	v_pk_mul_f32 v[176:177], v[176:177], s[76:77] op_sel_hi:[1,0]
	v_pk_mul_f32 v[178:179], v[178:179], s[76:77] op_sel_hi:[1,0]
	v_pk_mul_f32 v[180:181], v[180:181], s[76:77] op_sel_hi:[1,0]
	v_pk_fma_f32 v[110:111], v[110:111], 0.5, v[174:175] op_sel_hi:[1,0,1]
	v_pk_fma_f32 v[112:113], v[112:113], 0.5, v[176:177] op_sel_hi:[1,0,1]
	v_pk_fma_f32 v[114:115], v[114:115], 0.5, v[178:179] op_sel_hi:[1,0,1]
	v_pk_fma_f32 v[116:117], v[116:117], 0.5, v[180:181] op_sel_hi:[1,0,1]
	v_pk_add_f32 v[174:175], v[110:111], v[114:115]
	v_pk_add_f32 v[176:177], v[112:113], v[116:117]
	v_pk_mul_f32 v[178:179], v[110:111], v[110:111]
	v_pk_mul_f32 v[180:181], v[112:113], v[112:113]
	v_pk_fma_f32 v[178:179], v[114:115], v[114:115], v[178:179]
	v_pk_fma_f32 v[180:181], v[116:117], v[116:117], v[180:181]
	v_pk_add_f32 v[174:175], v[174:175], v[176:177]
	v_pk_add_f32 v[178:179], v[178:179], v[180:181]
	v_cvt_pk_bf16_f32 v212, v110, v111
	v_cvt_pk_bf16_f32 v213, v112, v113
	v_cvt_pk_bf16_f32 v214, v114, v115
	v_cvt_pk_bf16_f32 v215, v116, v117
	v_add_f32_e32 v5, v174, v175
	v_add_f32_e32 v187, v178, v179
	s_waitcnt vmcnt(4)
	v_lshlrev_b32_e32 v174, 16, v216
	v_and_b32_e32 v175, 0xffff0000, v216
	v_lshlrev_b32_e32 v176, 16, v217
	v_and_b32_e32 v177, 0xffff0000, v217
	v_lshlrev_b32_e32 v178, 16, v218
	v_and_b32_e32 v179, 0xffff0000, v218
	v_lshlrev_b32_e32 v180, 16, v219
	v_and_b32_e32 v181, 0xffff0000, v219
	v_pk_add_f32 v[174:175], v[174:175], v[148:149] op_sel_hi:[1,0] neg_lo:[0,1] neg_hi:[0,1]
	v_pk_add_f32 v[176:177], v[176:177], v[148:149] op_sel_hi:[1,0] neg_lo:[0,1] neg_hi:[0,1]
	v_pk_add_f32 v[178:179], v[178:179], v[148:149] op_sel_hi:[1,0] neg_lo:[0,1] neg_hi:[0,1]
	v_pk_add_f32 v[180:181], v[180:181], v[148:149] op_sel_hi:[1,0] neg_lo:[0,1] neg_hi:[0,1]
	v_pk_mul_f32 v[174:175], v[148:149], v[174:175] op_sel:[1,0] op_sel_hi:[1,1]
	v_pk_mul_f32 v[176:177], v[148:149], v[176:177] op_sel:[1,0] op_sel_hi:[1,1]
	v_pk_mul_f32 v[178:179], v[148:149], v[178:179] op_sel:[1,0] op_sel_hi:[1,1]
	v_pk_mul_f32 v[180:181], v[148:149], v[180:181] op_sel:[1,0] op_sel_hi:[1,1]
	v_pk_fma_f32 v[174:175], v[150:151], v[174:175], v[158:159]
	v_pk_fma_f32 v[176:177], v[152:153], v[176:177], v[160:161]
	v_pk_fma_f32 v[178:179], v[154:155], v[178:179], v[162:163]
	v_pk_fma_f32 v[180:181], v[156:157], v[180:181], v[164:165]
	v_pk_mul_f32 v[174:175], v[174:175], s[76:77] op_sel_hi:[1,0]
	v_pk_mul_f32 v[176:177], v[176:177], s[76:77] op_sel_hi:[1,0]
	v_pk_mul_f32 v[178:179], v[178:179], s[76:77] op_sel_hi:[1,0]
	v_pk_mul_f32 v[180:181], v[180:181], s[76:77] op_sel_hi:[1,0]
	v_pk_fma_f32 v[102:103], v[102:103], 0.5, v[174:175] op_sel_hi:[1,0,1]
	v_pk_fma_f32 v[104:105], v[104:105], 0.5, v[176:177] op_sel_hi:[1,0,1]
	v_pk_fma_f32 v[106:107], v[106:107], 0.5, v[178:179] op_sel_hi:[1,0,1]
	v_pk_fma_f32 v[108:109], v[108:109], 0.5, v[180:181] op_sel_hi:[1,0,1]
	v_pk_add_f32 v[174:175], v[102:103], v[106:107]
	v_pk_add_f32 v[176:177], v[104:105], v[108:109]
	v_pk_mul_f32 v[178:179], v[102:103], v[102:103]
	v_pk_mul_f32 v[180:181], v[104:105], v[104:105]
	v_pk_fma_f32 v[178:179], v[106:107], v[106:107], v[178:179]
	v_pk_fma_f32 v[180:181], v[108:109], v[108:109], v[180:181]
	v_pk_add_f32 v[174:175], v[174:175], v[176:177]
	v_pk_add_f32 v[178:179], v[178:179], v[180:181]
	v_cvt_pk_bf16_f32 v216, v102, v103
	v_cvt_pk_bf16_f32 v217, v104, v105
	v_cvt_pk_bf16_f32 v218, v106, v107
	v_cvt_pk_bf16_f32 v219, v108, v109
	v_add_f32_e32 v139, v174, v175
	v_add_f32_e32 v197, v178, v179
	global_load_dwordx4 v[102:105], v135, s[18:19]
	global_load_dwordx4 v[106:109], v135, s[6:7]
	global_load_dwordx4 v[110:113], v135, s[8:9]
	global_load_dwordx4 v[114:117], v135, s[10:11]
	global_load_dwordx4 v[118:121], v135, s[18:19] offset:256
	global_load_dwordx4 v[122:125], v135, s[6:7] offset:256
	global_load_dwordx4 v[126:129], v135, s[8:9] offset:256
	global_load_dwordx4 v[130:133], v135, s[10:11] offset:256
	global_store_dwordx4 v134, v[204:207], s[18:19]
	global_store_dwordx4 v134, v[208:211], s[6:7]
	global_store_dwordx4 v134, v[212:215], s[8:9]
	global_store_dwordx4 v134, v[216:219], s[10:11]
	ds_read_b128 v[150:153], v137 offset:512
	ds_read_b128 v[154:157], v137 offset:528
	ds_read_b128 v[158:161], v137 offset:1536
	ds_read_b128 v[162:165], v137 offset:1552
	s_waitcnt lgkmcnt(0)
	s_waitcnt vmcnt(15)
	v_lshlrev_b32_e32 v174, 16, v222
	v_and_b32_e32 v175, 0xffff0000, v222
	v_lshlrev_b32_e32 v176, 16, v223
	v_and_b32_e32 v177, 0xffff0000, v223
	v_lshlrev_b32_e32 v178, 16, v224
	v_and_b32_e32 v179, 0xffff0000, v224
	v_lshlrev_b32_e32 v180, 16, v225
	v_and_b32_e32 v181, 0xffff0000, v225
	v_pk_add_f32 v[174:175], v[174:175], v[142:143] op_sel_hi:[1,0] neg_lo:[0,1] neg_hi:[0,1]
	v_pk_add_f32 v[176:177], v[176:177], v[142:143] op_sel_hi:[1,0] neg_lo:[0,1] neg_hi:[0,1]
	v_pk_add_f32 v[178:179], v[178:179], v[142:143] op_sel_hi:[1,0] neg_lo:[0,1] neg_hi:[0,1]
	v_pk_add_f32 v[180:181], v[180:181], v[142:143] op_sel_hi:[1,0] neg_lo:[0,1] neg_hi:[0,1]
	v_pk_mul_f32 v[174:175], v[142:143], v[174:175] op_sel:[1,0] op_sel_hi:[1,1]
	v_pk_mul_f32 v[176:177], v[142:143], v[176:177] op_sel:[1,0] op_sel_hi:[1,1]
	v_pk_mul_f32 v[178:179], v[142:143], v[178:179] op_sel:[1,0] op_sel_hi:[1,1]
	v_pk_mul_f32 v[180:181], v[142:143], v[180:181] op_sel:[1,0] op_sel_hi:[1,1]
	v_pk_fma_f32 v[174:175], v[150:151], v[174:175], v[158:159]
	v_pk_fma_f32 v[176:177], v[152:153], v[176:177], v[160:161]
	v_pk_fma_f32 v[178:179], v[154:155], v[178:179], v[162:163]
	v_pk_fma_f32 v[180:181], v[156:157], v[180:181], v[164:165]
	v_pk_mul_f32 v[174:175], v[174:175], s[76:77] op_sel_hi:[1,0]
	v_pk_mul_f32 v[176:177], v[176:177], s[76:77] op_sel_hi:[1,0]
	v_pk_mul_f32 v[178:179], v[178:179], s[76:77] op_sel_hi:[1,0]
	v_pk_mul_f32 v[180:181], v[180:181], s[76:77] op_sel_hi:[1,0]
	v_pk_fma_f32 v[94:95], v[94:95], 0.5, v[174:175] op_sel_hi:[1,0,1]
	v_pk_fma_f32 v[96:97], v[96:97], 0.5, v[176:177] op_sel_hi:[1,0,1]
	v_pk_fma_f32 v[98:99], v[98:99], 0.5, v[178:179] op_sel_hi:[1,0,1]
	v_pk_fma_f32 v[100:101], v[100:101], 0.5, v[180:181] op_sel_hi:[1,0,1]
	v_pk_add_f32 v[174:175], v[94:95], v[98:99]
	v_pk_add_f32 v[176:177], v[96:97], v[100:101]
	v_pk_mul_f32 v[178:179], v[94:95], v[94:95]
	v_pk_mul_f32 v[180:181], v[96:97], v[96:97]
	v_pk_fma_f32 v[178:179], v[98:99], v[98:99], v[178:179]
	v_pk_fma_f32 v[180:181], v[100:101], v[100:101], v[180:181]
	v_pk_add_f32 v[174:175], v[174:175], v[176:177]
	v_pk_add_f32 v[178:179], v[178:179], v[180:181]
	v_cvt_pk_bf16_f32 v222, v94, v95
	v_cvt_pk_bf16_f32 v223, v96, v97
	v_cvt_pk_bf16_f32 v224, v98, v99
	v_cvt_pk_bf16_f32 v225, v100, v101
	v_add_f32_e32 v174, v174, v175
	v_add_f32_e32 v178, v178, v179
	v_add_f32_e32 v2, v2, v174
	v_add_f32_e32 v140, v140, v178
	s_waitcnt vmcnt(14)
	v_lshlrev_b32_e32 v174, 16, v182
	v_and_b32_e32 v175, 0xffff0000, v182
	v_lshlrev_b32_e32 v176, 16, v183
	v_and_b32_e32 v177, 0xffff0000, v183
	v_lshlrev_b32_e32 v178, 16, v184
	v_and_b32_e32 v179, 0xffff0000, v184
	v_lshlrev_b32_e32 v180, 16, v185
	v_and_b32_e32 v181, 0xffff0000, v185
	v_pk_add_f32 v[174:175], v[174:175], v[144:145] op_sel_hi:[1,0] neg_lo:[0,1] neg_hi:[0,1]
	v_pk_add_f32 v[176:177], v[176:177], v[144:145] op_sel_hi:[1,0] neg_lo:[0,1] neg_hi:[0,1]
	v_pk_add_f32 v[178:179], v[178:179], v[144:145] op_sel_hi:[1,0] neg_lo:[0,1] neg_hi:[0,1]
	v_pk_add_f32 v[180:181], v[180:181], v[144:145] op_sel_hi:[1,0] neg_lo:[0,1] neg_hi:[0,1]
	v_pk_mul_f32 v[174:175], v[144:145], v[174:175] op_sel:[1,0] op_sel_hi:[1,1]
	v_pk_mul_f32 v[176:177], v[144:145], v[176:177] op_sel:[1,0] op_sel_hi:[1,1]
	v_pk_mul_f32 v[178:179], v[144:145], v[178:179] op_sel:[1,0] op_sel_hi:[1,1]
	v_pk_mul_f32 v[180:181], v[144:145], v[180:181] op_sel:[1,0] op_sel_hi:[1,1]
	v_pk_fma_f32 v[174:175], v[150:151], v[174:175], v[158:159]
	v_pk_fma_f32 v[176:177], v[152:153], v[176:177], v[160:161]
	v_pk_fma_f32 v[178:179], v[154:155], v[178:179], v[162:163]
	v_pk_fma_f32 v[180:181], v[156:157], v[180:181], v[164:165]
	v_pk_mul_f32 v[174:175], v[174:175], s[76:77] op_sel_hi:[1,0]
	v_pk_mul_f32 v[176:177], v[176:177], s[76:77] op_sel_hi:[1,0]
	v_pk_mul_f32 v[178:179], v[178:179], s[76:77] op_sel_hi:[1,0]
	v_pk_mul_f32 v[180:181], v[180:181], s[76:77] op_sel_hi:[1,0]
	v_pk_fma_f32 v[86:87], v[86:87], 0.5, v[174:175] op_sel_hi:[1,0,1]
	v_pk_fma_f32 v[88:89], v[88:89], 0.5, v[176:177] op_sel_hi:[1,0,1]
	v_pk_fma_f32 v[90:91], v[90:91], 0.5, v[178:179] op_sel_hi:[1,0,1]
	v_pk_fma_f32 v[92:93], v[92:93], 0.5, v[180:181] op_sel_hi:[1,0,1]
	v_pk_add_f32 v[174:175], v[86:87], v[90:91]
	v_pk_add_f32 v[176:177], v[88:89], v[92:93]
	v_pk_mul_f32 v[178:179], v[86:87], v[86:87]
	v_pk_mul_f32 v[180:181], v[88:89], v[88:89]
	v_pk_fma_f32 v[178:179], v[90:91], v[90:91], v[178:179]
	v_pk_fma_f32 v[180:181], v[92:93], v[92:93], v[180:181]
	v_pk_add_f32 v[174:175], v[174:175], v[176:177]
	v_pk_add_f32 v[178:179], v[178:179], v[180:181]
	v_cvt_pk_bf16_f32 v182, v86, v87
	v_cvt_pk_bf16_f32 v183, v88, v89
	v_cvt_pk_bf16_f32 v184, v90, v91
	v_cvt_pk_bf16_f32 v185, v92, v93
	v_add_f32_e32 v174, v174, v175
	v_add_f32_e32 v178, v178, v179
	v_add_f32_e32 v4, v4, v174
	v_add_f32_e32 v186, v186, v178
	s_waitcnt vmcnt(13)
	v_lshlrev_b32_e32 v174, 16, v166
	v_and_b32_e32 v175, 0xffff0000, v166
	v_lshlrev_b32_e32 v176, 16, v167
	v_and_b32_e32 v177, 0xffff0000, v167
	v_lshlrev_b32_e32 v178, 16, v168
	v_and_b32_e32 v179, 0xffff0000, v168
	v_lshlrev_b32_e32 v180, 16, v169
	v_and_b32_e32 v181, 0xffff0000, v169
	v_pk_add_f32 v[174:175], v[174:175], v[146:147] op_sel_hi:[1,0] neg_lo:[0,1] neg_hi:[0,1]
	v_pk_add_f32 v[176:177], v[176:177], v[146:147] op_sel_hi:[1,0] neg_lo:[0,1] neg_hi:[0,1]
	v_pk_add_f32 v[178:179], v[178:179], v[146:147] op_sel_hi:[1,0] neg_lo:[0,1] neg_hi:[0,1]
	v_pk_add_f32 v[180:181], v[180:181], v[146:147] op_sel_hi:[1,0] neg_lo:[0,1] neg_hi:[0,1]
	v_pk_mul_f32 v[174:175], v[146:147], v[174:175] op_sel:[1,0] op_sel_hi:[1,1]
	v_pk_mul_f32 v[176:177], v[146:147], v[176:177] op_sel:[1,0] op_sel_hi:[1,1]
	v_pk_mul_f32 v[178:179], v[146:147], v[178:179] op_sel:[1,0] op_sel_hi:[1,1]
	v_pk_mul_f32 v[180:181], v[146:147], v[180:181] op_sel:[1,0] op_sel_hi:[1,1]
	v_pk_fma_f32 v[174:175], v[150:151], v[174:175], v[158:159]
	v_pk_fma_f32 v[176:177], v[152:153], v[176:177], v[160:161]
	v_pk_fma_f32 v[178:179], v[154:155], v[178:179], v[162:163]
	v_pk_fma_f32 v[180:181], v[156:157], v[180:181], v[164:165]
	v_pk_mul_f32 v[174:175], v[174:175], s[76:77] op_sel_hi:[1,0]
	v_pk_mul_f32 v[176:177], v[176:177], s[76:77] op_sel_hi:[1,0]
	v_pk_mul_f32 v[178:179], v[178:179], s[76:77] op_sel_hi:[1,0]
	v_pk_mul_f32 v[180:181], v[180:181], s[76:77] op_sel_hi:[1,0]
	v_pk_fma_f32 v[78:79], v[78:79], 0.5, v[174:175] op_sel_hi:[1,0,1]
	v_pk_fma_f32 v[80:81], v[80:81], 0.5, v[176:177] op_sel_hi:[1,0,1]
	v_pk_fma_f32 v[82:83], v[82:83], 0.5, v[178:179] op_sel_hi:[1,0,1]
	v_pk_fma_f32 v[84:85], v[84:85], 0.5, v[180:181] op_sel_hi:[1,0,1]
	v_pk_add_f32 v[174:175], v[78:79], v[82:83]
	v_pk_add_f32 v[176:177], v[80:81], v[84:85]
	v_pk_mul_f32 v[178:179], v[78:79], v[78:79]
	v_pk_mul_f32 v[180:181], v[80:81], v[80:81]
	v_pk_fma_f32 v[178:179], v[82:83], v[82:83], v[178:179]
	v_pk_fma_f32 v[180:181], v[84:85], v[84:85], v[180:181]
	v_pk_add_f32 v[174:175], v[174:175], v[176:177]
	v_pk_add_f32 v[178:179], v[178:179], v[180:181]
	v_cvt_pk_bf16_f32 v166, v78, v79
	v_cvt_pk_bf16_f32 v167, v80, v81
	v_cvt_pk_bf16_f32 v168, v82, v83
	v_cvt_pk_bf16_f32 v169, v84, v85
	v_add_f32_e32 v174, v174, v175
	v_add_f32_e32 v178, v178, v179
	v_add_f32_e32 v5, v5, v174
	v_add_f32_e32 v187, v187, v178
	s_waitcnt vmcnt(12)
	v_lshlrev_b32_e32 v174, 16, v170
	v_and_b32_e32 v175, 0xffff0000, v170
	v_lshlrev_b32_e32 v176, 16, v171
	v_and_b32_e32 v177, 0xffff0000, v171
	v_lshlrev_b32_e32 v178, 16, v172
	v_and_b32_e32 v179, 0xffff0000, v172
	v_lshlrev_b32_e32 v180, 16, v173
	v_and_b32_e32 v181, 0xffff0000, v173
	v_pk_add_f32 v[174:175], v[174:175], v[148:149] op_sel_hi:[1,0] neg_lo:[0,1] neg_hi:[0,1]
	v_pk_add_f32 v[176:177], v[176:177], v[148:149] op_sel_hi:[1,0] neg_lo:[0,1] neg_hi:[0,1]
	v_pk_add_f32 v[178:179], v[178:179], v[148:149] op_sel_hi:[1,0] neg_lo:[0,1] neg_hi:[0,1]
	v_pk_add_f32 v[180:181], v[180:181], v[148:149] op_sel_hi:[1,0] neg_lo:[0,1] neg_hi:[0,1]
	v_pk_mul_f32 v[174:175], v[148:149], v[174:175] op_sel:[1,0] op_sel_hi:[1,1]
	v_pk_mul_f32 v[176:177], v[148:149], v[176:177] op_sel:[1,0] op_sel_hi:[1,1]
	v_pk_mul_f32 v[178:179], v[148:149], v[178:179] op_sel:[1,0] op_sel_hi:[1,1]
	v_pk_mul_f32 v[180:181], v[148:149], v[180:181] op_sel:[1,0] op_sel_hi:[1,1]
	v_pk_fma_f32 v[174:175], v[150:151], v[174:175], v[158:159]
	v_pk_fma_f32 v[176:177], v[152:153], v[176:177], v[160:161]
	v_pk_fma_f32 v[178:179], v[154:155], v[178:179], v[162:163]
	v_pk_fma_f32 v[180:181], v[156:157], v[180:181], v[164:165]
	v_pk_mul_f32 v[174:175], v[174:175], s[76:77] op_sel_hi:[1,0]
	v_pk_mul_f32 v[176:177], v[176:177], s[76:77] op_sel_hi:[1,0]
	v_pk_mul_f32 v[178:179], v[178:179], s[76:77] op_sel_hi:[1,0]
	v_pk_mul_f32 v[180:181], v[180:181], s[76:77] op_sel_hi:[1,0]
	v_pk_fma_f32 v[70:71], v[70:71], 0.5, v[174:175] op_sel_hi:[1,0,1]
	v_pk_fma_f32 v[72:73], v[72:73], 0.5, v[176:177] op_sel_hi:[1,0,1]
	v_pk_fma_f32 v[74:75], v[74:75], 0.5, v[178:179] op_sel_hi:[1,0,1]
	v_pk_fma_f32 v[76:77], v[76:77], 0.5, v[180:181] op_sel_hi:[1,0,1]
	v_pk_add_f32 v[174:175], v[70:71], v[74:75]
	v_pk_add_f32 v[176:177], v[72:73], v[76:77]
	v_pk_mul_f32 v[178:179], v[70:71], v[70:71]
	v_pk_mul_f32 v[180:181], v[72:73], v[72:73]
	v_pk_fma_f32 v[178:179], v[74:75], v[74:75], v[178:179]
	v_pk_fma_f32 v[180:181], v[76:77], v[76:77], v[180:181]
	v_pk_add_f32 v[174:175], v[174:175], v[176:177]
	v_pk_add_f32 v[178:179], v[178:179], v[180:181]
	v_cvt_pk_bf16_f32 v170, v70, v71
	v_cvt_pk_bf16_f32 v171, v72, v73
	v_cvt_pk_bf16_f32 v172, v74, v75
	v_cvt_pk_bf16_f32 v173, v76, v77
	v_add_f32_e32 v174, v174, v175
	v_add_f32_e32 v178, v178, v179
	v_add_f32_e32 v139, v139, v174
	v_add_f32_e32 v197, v197, v178
	global_store_dwordx4 v134, v[222:225], s[18:19] offset:256
	global_store_dwordx4 v134, v[182:185], s[6:7] offset:256
	global_store_dwordx4 v134, v[166:169], s[8:9] offset:256
	global_store_dwordx4 v134, v[170:173], s[10:11] offset:256
	ds_bpermute_b32 v174, v201, v2
	ds_bpermute_b32 v175, v201, v4
	ds_bpermute_b32 v176, v201, v5
	ds_bpermute_b32 v177, v201, v139
	ds_bpermute_b32 v178, v201, v140
	ds_bpermute_b32 v179, v201, v186
	ds_bpermute_b32 v180, v201, v187
	ds_bpermute_b32 v181, v201, v197
	s_waitcnt lgkmcnt(0)
	v_add_f32_e32 v2, v2, v174
	v_add_f32_e32 v4, v4, v175
	v_add_f32_e32 v5, v5, v176
	v_add_f32_e32 v139, v139, v177
	v_add_f32_e32 v140, v140, v178
	v_add_f32_e32 v186, v186, v179
	v_add_f32_e32 v187, v187, v180
	v_add_f32_e32 v197, v197, v181
	ds_bpermute_b32 v174, v203, v2
	ds_bpermute_b32 v175, v203, v4
	ds_bpermute_b32 v176, v203, v5
	ds_bpermute_b32 v177, v203, v139
	ds_bpermute_b32 v178, v203, v140
	ds_bpermute_b32 v179, v203, v186
	ds_bpermute_b32 v180, v203, v187
	ds_bpermute_b32 v181, v203, v197
	s_waitcnt lgkmcnt(0)
	v_add_f32_e32 v2, v2, v174
	v_add_f32_e32 v4, v4, v175
	v_add_f32_e32 v5, v5, v176
	v_add_f32_e32 v139, v139, v177
	v_add_f32_e32 v140, v140, v178
	v_add_f32_e32 v186, v186, v179
	v_add_f32_e32 v187, v187, v180
	v_add_f32_e32 v197, v197, v181
	v_cmp_eq_u32_e32 vcc, 1, v191
	s_nop 1
	v_cndmask_b32_e32 v2, v2, v4, vcc
	v_cndmask_b32_e32 v140, v140, v186, vcc
	v_cmp_eq_u32_e32 vcc, 2, v191
	s_nop 1
	v_cndmask_b32_e32 v2, v2, v5, vcc
	v_cndmask_b32_e32 v140, v140, v187, vcc
	v_cmp_eq_u32_e32 vcc, 3, v191
	s_nop 1
	v_cndmask_b32_e32 v2, v2, v139, vcc
	v_cndmask_b32_e32 v140, v140, v197, vcc
	global_atomic_add_f32 v138, v2, s[16:17]
	global_atomic_add_f32 v138, v140, s[16:17] offset:4
	ds_read2_b64 v[142:145], v136 offset0:128 offset1:144
	ds_read2_b64 v[146:149], v136 offset0:160 offset1:176
	ds_read_b128 v[150:153], v137
	ds_read_b128 v[154:157], v137 offset:16
	ds_read_b128 v[158:161], v137 offset:1024
	ds_read_b128 v[162:165], v137 offset:1040
	s_waitcnt lgkmcnt(0)
	v_mul_f32_e32 v142, 0x3a000000, v142
	v_mul_f32_e32 v174, v142, v142
	v_fma_f32 v174, v143, s72, -v174
	v_add_f32_e32 v174, 0x3727c5ac, v174
	v_mul_f32_e32 v144, 0x3a000000, v144
	v_mul_f32_e32 v175, v144, v144
	v_fma_f32 v175, v145, s72, -v175
	v_add_f32_e32 v175, 0x3727c5ac, v175
	v_mul_f32_e32 v146, 0x3a000000, v146
	v_mul_f32_e32 v176, v146, v146
	v_fma_f32 v176, v147, s72, -v176
	v_add_f32_e32 v176, 0x3727c5ac, v176
	v_mul_f32_e32 v148, 0x3a000000, v148
	v_mul_f32_e32 v177, v148, v148
	v_fma_f32 v177, v149, s72, -v177
	v_add_f32_e32 v177, 0x3727c5ac, v177
	v_rsq_f32_e32 v143, v174
	v_rsq_f32_e32 v145, v175
	v_rsq_f32_e32 v147, v176
	v_rsq_f32_e32 v149, v177
	s_nop 0
	s_waitcnt vmcnt(17)
	v_lshlrev_b32_e32 v174, 16, v102
	v_and_b32_e32 v175, 0xffff0000, v102
	v_lshlrev_b32_e32 v176, 16, v103
	v_and_b32_e32 v177, 0xffff0000, v103
	v_lshlrev_b32_e32 v178, 16, v104
	v_and_b32_e32 v179, 0xffff0000, v104
	v_lshlrev_b32_e32 v180, 16, v105
	v_and_b32_e32 v181, 0xffff0000, v105
	v_pk_add_f32 v[174:175], v[174:175], v[142:143] op_sel_hi:[1,0] neg_lo:[0,1] neg_hi:[0,1]
	v_pk_add_f32 v[176:177], v[176:177], v[142:143] op_sel_hi:[1,0] neg_lo:[0,1] neg_hi:[0,1]
	v_pk_add_f32 v[178:179], v[178:179], v[142:143] op_sel_hi:[1,0] neg_lo:[0,1] neg_hi:[0,1]
	v_pk_add_f32 v[180:181], v[180:181], v[142:143] op_sel_hi:[1,0] neg_lo:[0,1] neg_hi:[0,1]
	v_pk_mul_f32 v[174:175], v[142:143], v[174:175] op_sel:[1,0] op_sel_hi:[1,1]
	v_pk_mul_f32 v[176:177], v[142:143], v[176:177] op_sel:[1,0] op_sel_hi:[1,1]
	v_pk_mul_f32 v[178:179], v[142:143], v[178:179] op_sel:[1,0] op_sel_hi:[1,1]
	v_pk_mul_f32 v[180:181], v[142:143], v[180:181] op_sel:[1,0] op_sel_hi:[1,1]
	v_pk_fma_f32 v[174:175], v[150:151], v[174:175], v[158:159]
	v_pk_fma_f32 v[176:177], v[152:153], v[176:177], v[160:161]
	v_pk_fma_f32 v[178:179], v[154:155], v[178:179], v[162:163]
	v_pk_fma_f32 v[180:181], v[156:157], v[180:181], v[164:165]
	v_pk_mul_f32 v[174:175], v[174:175], s[76:77] op_sel_hi:[1,0]
	v_pk_mul_f32 v[176:177], v[176:177], s[76:77] op_sel_hi:[1,0]
	v_pk_mul_f32 v[178:179], v[178:179], s[76:77] op_sel_hi:[1,0]
	v_pk_mul_f32 v[180:181], v[180:181], s[76:77] op_sel_hi:[1,0]
	v_pk_fma_f32 v[46:47], v[46:47], 0.5, v[174:175] op_sel_hi:[1,0,1]
	v_pk_fma_f32 v[48:49], v[48:49], 0.5, v[176:177] op_sel_hi:[1,0,1]
	v_pk_fma_f32 v[50:51], v[50:51], 0.5, v[178:179] op_sel_hi:[1,0,1]
	v_pk_fma_f32 v[52:53], v[52:53], 0.5, v[180:181] op_sel_hi:[1,0,1]
	v_pk_add_f32 v[174:175], v[46:47], v[50:51]
	v_pk_add_f32 v[176:177], v[48:49], v[52:53]
	v_pk_mul_f32 v[178:179], v[46:47], v[46:47]
	v_pk_mul_f32 v[180:181], v[48:49], v[48:49]
	v_pk_fma_f32 v[178:179], v[50:51], v[50:51], v[178:179]
	v_pk_fma_f32 v[180:181], v[52:53], v[52:53], v[180:181]
	v_pk_add_f32 v[174:175], v[174:175], v[176:177]
	v_pk_add_f32 v[178:179], v[178:179], v[180:181]
	v_cvt_pk_bf16_f32 v102, v46, v47
	v_cvt_pk_bf16_f32 v103, v48, v49
	v_cvt_pk_bf16_f32 v104, v50, v51
	v_cvt_pk_bf16_f32 v105, v52, v53
	v_add_f32_e32 v2, v174, v175
	v_add_f32_e32 v140, v178, v179
	s_waitcnt vmcnt(16)
	v_lshlrev_b32_e32 v174, 16, v106
	v_and_b32_e32 v175, 0xffff0000, v106
	v_lshlrev_b32_e32 v176, 16, v107
	v_and_b32_e32 v177, 0xffff0000, v107
	v_lshlrev_b32_e32 v178, 16, v108
	v_and_b32_e32 v179, 0xffff0000, v108
	v_lshlrev_b32_e32 v180, 16, v109
	v_and_b32_e32 v181, 0xffff0000, v109
	v_pk_add_f32 v[174:175], v[174:175], v[144:145] op_sel_hi:[1,0] neg_lo:[0,1] neg_hi:[0,1]
	v_pk_add_f32 v[176:177], v[176:177], v[144:145] op_sel_hi:[1,0] neg_lo:[0,1] neg_hi:[0,1]
	v_pk_add_f32 v[178:179], v[178:179], v[144:145] op_sel_hi:[1,0] neg_lo:[0,1] neg_hi:[0,1]
	v_pk_add_f32 v[180:181], v[180:181], v[144:145] op_sel_hi:[1,0] neg_lo:[0,1] neg_hi:[0,1]
	v_pk_mul_f32 v[174:175], v[144:145], v[174:175] op_sel:[1,0] op_sel_hi:[1,1]
	v_pk_mul_f32 v[176:177], v[144:145], v[176:177] op_sel:[1,0] op_sel_hi:[1,1]
	v_pk_mul_f32 v[178:179], v[144:145], v[178:179] op_sel:[1,0] op_sel_hi:[1,1]
	v_pk_mul_f32 v[180:181], v[144:145], v[180:181] op_sel:[1,0] op_sel_hi:[1,1]
	v_pk_fma_f32 v[174:175], v[150:151], v[174:175], v[158:159]
	v_pk_fma_f32 v[176:177], v[152:153], v[176:177], v[160:161]
	v_pk_fma_f32 v[178:179], v[154:155], v[178:179], v[162:163]
	v_pk_fma_f32 v[180:181], v[156:157], v[180:181], v[164:165]
	v_pk_mul_f32 v[174:175], v[174:175], s[76:77] op_sel_hi:[1,0]
	v_pk_mul_f32 v[176:177], v[176:177], s[76:77] op_sel_hi:[1,0]
	v_pk_mul_f32 v[178:179], v[178:179], s[76:77] op_sel_hi:[1,0]
	v_pk_mul_f32 v[180:181], v[180:181], s[76:77] op_sel_hi:[1,0]
	v_pk_fma_f32 v[38:39], v[38:39], 0.5, v[174:175] op_sel_hi:[1,0,1]
	v_pk_fma_f32 v[40:41], v[40:41], 0.5, v[176:177] op_sel_hi:[1,0,1]
	v_pk_fma_f32 v[42:43], v[42:43], 0.5, v[178:179] op_sel_hi:[1,0,1]
	v_pk_fma_f32 v[44:45], v[44:45], 0.5, v[180:181] op_sel_hi:[1,0,1]
	v_pk_add_f32 v[174:175], v[38:39], v[42:43]
	v_pk_add_f32 v[176:177], v[40:41], v[44:45]
	v_pk_mul_f32 v[178:179], v[38:39], v[38:39]
	v_pk_mul_f32 v[180:181], v[40:41], v[40:41]
	v_pk_fma_f32 v[178:179], v[42:43], v[42:43], v[178:179]
	v_pk_fma_f32 v[180:181], v[44:45], v[44:45], v[180:181]
	v_pk_add_f32 v[174:175], v[174:175], v[176:177]
	v_pk_add_f32 v[178:179], v[178:179], v[180:181]
	v_cvt_pk_bf16_f32 v106, v38, v39
	v_cvt_pk_bf16_f32 v107, v40, v41
	v_cvt_pk_bf16_f32 v108, v42, v43
	v_cvt_pk_bf16_f32 v109, v44, v45
	v_add_f32_e32 v4, v174, v175
	v_add_f32_e32 v186, v178, v179
	s_waitcnt vmcnt(15)
	v_lshlrev_b32_e32 v174, 16, v110
	v_and_b32_e32 v175, 0xffff0000, v110
	v_lshlrev_b32_e32 v176, 16, v111
	v_and_b32_e32 v177, 0xffff0000, v111
	v_lshlrev_b32_e32 v178, 16, v112
	v_and_b32_e32 v179, 0xffff0000, v112
	v_lshlrev_b32_e32 v180, 16, v113
	v_and_b32_e32 v181, 0xffff0000, v113
	v_pk_add_f32 v[174:175], v[174:175], v[146:147] op_sel_hi:[1,0] neg_lo:[0,1] neg_hi:[0,1]
	v_pk_add_f32 v[176:177], v[176:177], v[146:147] op_sel_hi:[1,0] neg_lo:[0,1] neg_hi:[0,1]
	v_pk_add_f32 v[178:179], v[178:179], v[146:147] op_sel_hi:[1,0] neg_lo:[0,1] neg_hi:[0,1]
	v_pk_add_f32 v[180:181], v[180:181], v[146:147] op_sel_hi:[1,0] neg_lo:[0,1] neg_hi:[0,1]
	v_pk_mul_f32 v[174:175], v[146:147], v[174:175] op_sel:[1,0] op_sel_hi:[1,1]
	v_pk_mul_f32 v[176:177], v[146:147], v[176:177] op_sel:[1,0] op_sel_hi:[1,1]
	v_pk_mul_f32 v[178:179], v[146:147], v[178:179] op_sel:[1,0] op_sel_hi:[1,1]
	v_pk_mul_f32 v[180:181], v[146:147], v[180:181] op_sel:[1,0] op_sel_hi:[1,1]
	v_pk_fma_f32 v[174:175], v[150:151], v[174:175], v[158:159]
	v_pk_fma_f32 v[176:177], v[152:153], v[176:177], v[160:161]
	v_pk_fma_f32 v[178:179], v[154:155], v[178:179], v[162:163]
	v_pk_fma_f32 v[180:181], v[156:157], v[180:181], v[164:165]
	v_pk_mul_f32 v[174:175], v[174:175], s[76:77] op_sel_hi:[1,0]
	v_pk_mul_f32 v[176:177], v[176:177], s[76:77] op_sel_hi:[1,0]
	v_pk_mul_f32 v[178:179], v[178:179], s[76:77] op_sel_hi:[1,0]
	v_pk_mul_f32 v[180:181], v[180:181], s[76:77] op_sel_hi:[1,0]
	v_pk_fma_f32 v[30:31], v[30:31], 0.5, v[174:175] op_sel_hi:[1,0,1]
	v_pk_fma_f32 v[32:33], v[32:33], 0.5, v[176:177] op_sel_hi:[1,0,1]
	v_pk_fma_f32 v[34:35], v[34:35], 0.5, v[178:179] op_sel_hi:[1,0,1]
	v_pk_fma_f32 v[36:37], v[36:37], 0.5, v[180:181] op_sel_hi:[1,0,1]
	v_pk_add_f32 v[174:175], v[30:31], v[34:35]
	v_pk_add_f32 v[176:177], v[32:33], v[36:37]
	v_pk_mul_f32 v[178:179], v[30:31], v[30:31]
	v_pk_mul_f32 v[180:181], v[32:33], v[32:33]
	v_pk_fma_f32 v[178:179], v[34:35], v[34:35], v[178:179]
	v_pk_fma_f32 v[180:181], v[36:37], v[36:37], v[180:181]
	v_pk_add_f32 v[174:175], v[174:175], v[176:177]
	v_pk_add_f32 v[178:179], v[178:179], v[180:181]
	v_cvt_pk_bf16_f32 v110, v30, v31
	v_cvt_pk_bf16_f32 v111, v32, v33
	v_cvt_pk_bf16_f32 v112, v34, v35
	v_cvt_pk_bf16_f32 v113, v36, v37
	v_add_f32_e32 v5, v174, v175
	v_add_f32_e32 v187, v178, v179
	s_waitcnt vmcnt(14)
	v_lshlrev_b32_e32 v174, 16, v114
	v_and_b32_e32 v175, 0xffff0000, v114
	v_lshlrev_b32_e32 v176, 16, v115
	v_and_b32_e32 v177, 0xffff0000, v115
	v_lshlrev_b32_e32 v178, 16, v116
	v_and_b32_e32 v179, 0xffff0000, v116
	v_lshlrev_b32_e32 v180, 16, v117
	v_and_b32_e32 v181, 0xffff0000, v117
	v_pk_add_f32 v[174:175], v[174:175], v[148:149] op_sel_hi:[1,0] neg_lo:[0,1] neg_hi:[0,1]
	v_pk_add_f32 v[176:177], v[176:177], v[148:149] op_sel_hi:[1,0] neg_lo:[0,1] neg_hi:[0,1]
	v_pk_add_f32 v[178:179], v[178:179], v[148:149] op_sel_hi:[1,0] neg_lo:[0,1] neg_hi:[0,1]
	v_pk_add_f32 v[180:181], v[180:181], v[148:149] op_sel_hi:[1,0] neg_lo:[0,1] neg_hi:[0,1]
	v_pk_mul_f32 v[174:175], v[148:149], v[174:175] op_sel:[1,0] op_sel_hi:[1,1]
	v_pk_mul_f32 v[176:177], v[148:149], v[176:177] op_sel:[1,0] op_sel_hi:[1,1]
	v_pk_mul_f32 v[178:179], v[148:149], v[178:179] op_sel:[1,0] op_sel_hi:[1,1]
	v_pk_mul_f32 v[180:181], v[148:149], v[180:181] op_sel:[1,0] op_sel_hi:[1,1]
	v_pk_fma_f32 v[174:175], v[150:151], v[174:175], v[158:159]
	v_pk_fma_f32 v[176:177], v[152:153], v[176:177], v[160:161]
	v_pk_fma_f32 v[178:179], v[154:155], v[178:179], v[162:163]
	v_pk_fma_f32 v[180:181], v[156:157], v[180:181], v[164:165]
	v_pk_mul_f32 v[174:175], v[174:175], s[76:77] op_sel_hi:[1,0]
	v_pk_mul_f32 v[176:177], v[176:177], s[76:77] op_sel_hi:[1,0]
	v_pk_mul_f32 v[178:179], v[178:179], s[76:77] op_sel_hi:[1,0]
	v_pk_mul_f32 v[180:181], v[180:181], s[76:77] op_sel_hi:[1,0]
	v_pk_fma_f32 v[22:23], v[22:23], 0.5, v[174:175] op_sel_hi:[1,0,1]
	v_pk_fma_f32 v[24:25], v[24:25], 0.5, v[176:177] op_sel_hi:[1,0,1]
	v_pk_fma_f32 v[26:27], v[26:27], 0.5, v[178:179] op_sel_hi:[1,0,1]
	v_pk_fma_f32 v[28:29], v[28:29], 0.5, v[180:181] op_sel_hi:[1,0,1]
	v_pk_add_f32 v[174:175], v[22:23], v[26:27]
	v_pk_add_f32 v[176:177], v[24:25], v[28:29]
	v_pk_mul_f32 v[178:179], v[22:23], v[22:23]
	v_pk_mul_f32 v[180:181], v[24:25], v[24:25]
	v_pk_fma_f32 v[178:179], v[26:27], v[26:27], v[178:179]
	v_pk_fma_f32 v[180:181], v[28:29], v[28:29], v[180:181]
	v_pk_add_f32 v[174:175], v[174:175], v[176:177]
	v_pk_add_f32 v[178:179], v[178:179], v[180:181]
	v_cvt_pk_bf16_f32 v114, v22, v23
	v_cvt_pk_bf16_f32 v115, v24, v25
	v_cvt_pk_bf16_f32 v116, v26, v27
	v_cvt_pk_bf16_f32 v117, v28, v29
	v_add_f32_e32 v139, v174, v175
	v_add_f32_e32 v197, v178, v179
	global_store_dwordx4 v135, v[102:105], s[18:19]
	global_store_dwordx4 v135, v[106:109], s[6:7]
	global_store_dwordx4 v135, v[110:113], s[8:9]
	global_store_dwordx4 v135, v[114:117], s[10:11]
	ds_read_b128 v[150:153], v137 offset:512
	ds_read_b128 v[154:157], v137 offset:528
	ds_read_b128 v[158:161], v137 offset:1536
	ds_read_b128 v[162:165], v137 offset:1552
	s_waitcnt lgkmcnt(0)
	s_waitcnt vmcnt(17)
	v_lshlrev_b32_e32 v174, 16, v118
	v_and_b32_e32 v175, 0xffff0000, v118
	v_lshlrev_b32_e32 v176, 16, v119
	v_and_b32_e32 v177, 0xffff0000, v119
	v_lshlrev_b32_e32 v178, 16, v120
	v_and_b32_e32 v179, 0xffff0000, v120
	v_lshlrev_b32_e32 v180, 16, v121
	v_and_b32_e32 v181, 0xffff0000, v121
	v_pk_add_f32 v[174:175], v[174:175], v[142:143] op_sel_hi:[1,0] neg_lo:[0,1] neg_hi:[0,1]
	v_pk_add_f32 v[176:177], v[176:177], v[142:143] op_sel_hi:[1,0] neg_lo:[0,1] neg_hi:[0,1]
	v_pk_add_f32 v[178:179], v[178:179], v[142:143] op_sel_hi:[1,0] neg_lo:[0,1] neg_hi:[0,1]
	v_pk_add_f32 v[180:181], v[180:181], v[142:143] op_sel_hi:[1,0] neg_lo:[0,1] neg_hi:[0,1]
	v_pk_mul_f32 v[174:175], v[142:143], v[174:175] op_sel:[1,0] op_sel_hi:[1,1]
	v_pk_mul_f32 v[176:177], v[142:143], v[176:177] op_sel:[1,0] op_sel_hi:[1,1]
	v_pk_mul_f32 v[178:179], v[142:143], v[178:179] op_sel:[1,0] op_sel_hi:[1,1]
	v_pk_mul_f32 v[180:181], v[142:143], v[180:181] op_sel:[1,0] op_sel_hi:[1,1]
	v_pk_fma_f32 v[174:175], v[150:151], v[174:175], v[158:159]
	v_pk_fma_f32 v[176:177], v[152:153], v[176:177], v[160:161]
	v_pk_fma_f32 v[178:179], v[154:155], v[178:179], v[162:163]
	v_pk_fma_f32 v[180:181], v[156:157], v[180:181], v[164:165]
	v_pk_mul_f32 v[174:175], v[174:175], s[76:77] op_sel_hi:[1,0]
	v_pk_mul_f32 v[176:177], v[176:177], s[76:77] op_sel_hi:[1,0]
	v_pk_mul_f32 v[178:179], v[178:179], s[76:77] op_sel_hi:[1,0]
	v_pk_mul_f32 v[180:181], v[180:181], s[76:77] op_sel_hi:[1,0]
	v_pk_fma_f32 v[14:15], v[14:15], 0.5, v[174:175] op_sel_hi:[1,0,1]
	v_pk_fma_f32 v[16:17], v[16:17], 0.5, v[176:177] op_sel_hi:[1,0,1]
	v_pk_fma_f32 v[18:19], v[18:19], 0.5, v[178:179] op_sel_hi:[1,0,1]
	v_pk_fma_f32 v[20:21], v[20:21], 0.5, v[180:181] op_sel_hi:[1,0,1]
	v_pk_add_f32 v[174:175], v[14:15], v[18:19]
	v_pk_add_f32 v[176:177], v[16:17], v[20:21]
	v_pk_mul_f32 v[178:179], v[14:15], v[14:15]
	v_pk_mul_f32 v[180:181], v[16:17], v[16:17]
	v_pk_fma_f32 v[178:179], v[18:19], v[18:19], v[178:179]
	v_pk_fma_f32 v[180:181], v[20:21], v[20:21], v[180:181]
	v_pk_add_f32 v[174:175], v[174:175], v[176:177]
	v_pk_add_f32 v[178:179], v[178:179], v[180:181]
	v_cvt_pk_bf16_f32 v118, v14, v15
	v_cvt_pk_bf16_f32 v119, v16, v17
	v_cvt_pk_bf16_f32 v120, v18, v19
	v_cvt_pk_bf16_f32 v121, v20, v21
	v_add_f32_e32 v174, v174, v175
	v_add_f32_e32 v178, v178, v179
	v_add_f32_e32 v2, v2, v174
	v_add_f32_e32 v140, v140, v178
	s_waitcnt vmcnt(16)
	v_lshlrev_b32_e32 v174, 16, v122
	v_and_b32_e32 v175, 0xffff0000, v122
	v_lshlrev_b32_e32 v176, 16, v123
	v_and_b32_e32 v177, 0xffff0000, v123
	v_lshlrev_b32_e32 v178, 16, v124
	v_and_b32_e32 v179, 0xffff0000, v124
	v_lshlrev_b32_e32 v180, 16, v125
	v_and_b32_e32 v181, 0xffff0000, v125
	v_pk_add_f32 v[174:175], v[174:175], v[144:145] op_sel_hi:[1,0] neg_lo:[0,1] neg_hi:[0,1]
	v_pk_add_f32 v[176:177], v[176:177], v[144:145] op_sel_hi:[1,0] neg_lo:[0,1] neg_hi:[0,1]
	v_pk_add_f32 v[178:179], v[178:179], v[144:145] op_sel_hi:[1,0] neg_lo:[0,1] neg_hi:[0,1]
	v_pk_add_f32 v[180:181], v[180:181], v[144:145] op_sel_hi:[1,0] neg_lo:[0,1] neg_hi:[0,1]
	v_pk_mul_f32 v[174:175], v[144:145], v[174:175] op_sel:[1,0] op_sel_hi:[1,1]
	v_pk_mul_f32 v[176:177], v[144:145], v[176:177] op_sel:[1,0] op_sel_hi:[1,1]
	v_pk_mul_f32 v[178:179], v[144:145], v[178:179] op_sel:[1,0] op_sel_hi:[1,1]
	v_pk_mul_f32 v[180:181], v[144:145], v[180:181] op_sel:[1,0] op_sel_hi:[1,1]
	v_pk_fma_f32 v[174:175], v[150:151], v[174:175], v[158:159]
	v_pk_fma_f32 v[176:177], v[152:153], v[176:177], v[160:161]
	v_pk_fma_f32 v[178:179], v[154:155], v[178:179], v[162:163]
	v_pk_fma_f32 v[180:181], v[156:157], v[180:181], v[164:165]
	v_pk_mul_f32 v[174:175], v[174:175], s[76:77] op_sel_hi:[1,0]
	v_pk_mul_f32 v[176:177], v[176:177], s[76:77] op_sel_hi:[1,0]
	v_pk_mul_f32 v[178:179], v[178:179], s[76:77] op_sel_hi:[1,0]
	v_pk_mul_f32 v[180:181], v[180:181], s[76:77] op_sel_hi:[1,0]
	v_pk_fma_f32 v[6:7], v[6:7], 0.5, v[174:175] op_sel_hi:[1,0,1]
	v_pk_fma_f32 v[8:9], v[8:9], 0.5, v[176:177] op_sel_hi:[1,0,1]
	v_pk_fma_f32 v[10:11], v[10:11], 0.5, v[178:179] op_sel_hi:[1,0,1]
	v_pk_fma_f32 v[12:13], v[12:13], 0.5, v[180:181] op_sel_hi:[1,0,1]
	v_pk_add_f32 v[174:175], v[6:7], v[10:11]
	v_pk_add_f32 v[176:177], v[8:9], v[12:13]
	v_pk_mul_f32 v[178:179], v[6:7], v[6:7]
	v_pk_mul_f32 v[180:181], v[8:9], v[8:9]
	v_pk_fma_f32 v[178:179], v[10:11], v[10:11], v[178:179]
	v_pk_fma_f32 v[180:181], v[12:13], v[12:13], v[180:181]
	v_pk_add_f32 v[174:175], v[174:175], v[176:177]
	v_pk_add_f32 v[178:179], v[178:179], v[180:181]
	v_cvt_pk_bf16_f32 v122, v6, v7
	v_cvt_pk_bf16_f32 v123, v8, v9
	v_cvt_pk_bf16_f32 v124, v10, v11
	v_cvt_pk_bf16_f32 v125, v12, v13
	v_add_f32_e32 v174, v174, v175
	v_add_f32_e32 v178, v178, v179
	v_add_f32_e32 v4, v4, v174
	v_add_f32_e32 v186, v186, v178
	s_waitcnt vmcnt(15)
	v_lshlrev_b32_e32 v174, 16, v126
	v_and_b32_e32 v175, 0xffff0000, v126
	v_lshlrev_b32_e32 v176, 16, v127
	v_and_b32_e32 v177, 0xffff0000, v127
	v_lshlrev_b32_e32 v178, 16, v128
	v_and_b32_e32 v179, 0xffff0000, v128
	v_lshlrev_b32_e32 v180, 16, v129
	v_and_b32_e32 v181, 0xffff0000, v129
	v_pk_add_f32 v[174:175], v[174:175], v[146:147] op_sel_hi:[1,0] neg_lo:[0,1] neg_hi:[0,1]
	v_pk_add_f32 v[176:177], v[176:177], v[146:147] op_sel_hi:[1,0] neg_lo:[0,1] neg_hi:[0,1]
	v_pk_add_f32 v[178:179], v[178:179], v[146:147] op_sel_hi:[1,0] neg_lo:[0,1] neg_hi:[0,1]
	v_pk_add_f32 v[180:181], v[180:181], v[146:147] op_sel_hi:[1,0] neg_lo:[0,1] neg_hi:[0,1]
	v_pk_mul_f32 v[174:175], v[146:147], v[174:175] op_sel:[1,0] op_sel_hi:[1,1]
	v_pk_mul_f32 v[176:177], v[146:147], v[176:177] op_sel:[1,0] op_sel_hi:[1,1]
	v_pk_mul_f32 v[178:179], v[146:147], v[178:179] op_sel:[1,0] op_sel_hi:[1,1]
	v_pk_mul_f32 v[180:181], v[146:147], v[180:181] op_sel:[1,0] op_sel_hi:[1,1]
	v_pk_fma_f32 v[174:175], v[150:151], v[174:175], v[158:159]
	v_pk_fma_f32 v[176:177], v[152:153], v[176:177], v[160:161]
	v_pk_fma_f32 v[178:179], v[154:155], v[178:179], v[162:163]
	v_pk_fma_f32 v[180:181], v[156:157], v[180:181], v[164:165]
	v_pk_mul_f32 v[174:175], v[174:175], s[76:77] op_sel_hi:[1,0]
	v_pk_mul_f32 v[176:177], v[176:177], s[76:77] op_sel_hi:[1,0]
	v_pk_mul_f32 v[178:179], v[178:179], s[76:77] op_sel_hi:[1,0]
	v_pk_mul_f32 v[180:181], v[180:181], s[76:77] op_sel_hi:[1,0]
	v_pk_fma_f32 v[54:55], v[54:55], 0.5, v[174:175] op_sel_hi:[1,0,1]
	v_pk_fma_f32 v[56:57], v[56:57], 0.5, v[176:177] op_sel_hi:[1,0,1]
	v_pk_fma_f32 v[62:63], v[62:63], 0.5, v[178:179] op_sel_hi:[1,0,1]
	v_pk_fma_f32 v[64:65], v[64:65], 0.5, v[180:181] op_sel_hi:[1,0,1]
	v_pk_add_f32 v[174:175], v[54:55], v[62:63]
	v_pk_add_f32 v[176:177], v[56:57], v[64:65]
	v_pk_mul_f32 v[178:179], v[54:55], v[54:55]
	v_pk_mul_f32 v[180:181], v[56:57], v[56:57]
	v_pk_fma_f32 v[178:179], v[62:63], v[62:63], v[178:179]
	v_pk_fma_f32 v[180:181], v[64:65], v[64:65], v[180:181]
	v_pk_add_f32 v[174:175], v[174:175], v[176:177]
	v_pk_add_f32 v[178:179], v[178:179], v[180:181]
	v_cvt_pk_bf16_f32 v126, v54, v55
	v_cvt_pk_bf16_f32 v127, v56, v57
	v_cvt_pk_bf16_f32 v128, v62, v63
	v_cvt_pk_bf16_f32 v129, v64, v65
	v_add_f32_e32 v174, v174, v175
	v_add_f32_e32 v178, v178, v179
	v_add_f32_e32 v5, v5, v174
	v_add_f32_e32 v187, v187, v178
	s_waitcnt vmcnt(14)
	v_lshlrev_b32_e32 v174, 16, v130
	v_and_b32_e32 v175, 0xffff0000, v130
	v_lshlrev_b32_e32 v176, 16, v131
	v_and_b32_e32 v177, 0xffff0000, v131
	v_lshlrev_b32_e32 v178, 16, v132
	v_and_b32_e32 v179, 0xffff0000, v132
	v_lshlrev_b32_e32 v180, 16, v133
	v_and_b32_e32 v181, 0xffff0000, v133
	v_pk_add_f32 v[174:175], v[174:175], v[148:149] op_sel_hi:[1,0] neg_lo:[0,1] neg_hi:[0,1]
	v_pk_add_f32 v[176:177], v[176:177], v[148:149] op_sel_hi:[1,0] neg_lo:[0,1] neg_hi:[0,1]
	v_pk_add_f32 v[178:179], v[178:179], v[148:149] op_sel_hi:[1,0] neg_lo:[0,1] neg_hi:[0,1]
	v_pk_add_f32 v[180:181], v[180:181], v[148:149] op_sel_hi:[1,0] neg_lo:[0,1] neg_hi:[0,1]
	v_pk_mul_f32 v[174:175], v[148:149], v[174:175] op_sel:[1,0] op_sel_hi:[1,1]
	v_pk_mul_f32 v[176:177], v[148:149], v[176:177] op_sel:[1,0] op_sel_hi:[1,1]
	v_pk_mul_f32 v[178:179], v[148:149], v[178:179] op_sel:[1,0] op_sel_hi:[1,1]
	v_pk_mul_f32 v[180:181], v[148:149], v[180:181] op_sel:[1,0] op_sel_hi:[1,1]
	v_pk_fma_f32 v[174:175], v[150:151], v[174:175], v[158:159]
	v_pk_fma_f32 v[176:177], v[152:153], v[176:177], v[160:161]
	v_pk_fma_f32 v[178:179], v[154:155], v[178:179], v[162:163]
	v_pk_fma_f32 v[180:181], v[156:157], v[180:181], v[164:165]
	v_pk_mul_f32 v[174:175], v[174:175], s[76:77] op_sel_hi:[1,0]
	v_pk_mul_f32 v[176:177], v[176:177], s[76:77] op_sel_hi:[1,0]
	v_pk_mul_f32 v[178:179], v[178:179], s[76:77] op_sel_hi:[1,0]
	v_pk_mul_f32 v[180:181], v[180:181], s[76:77] op_sel_hi:[1,0]
	v_pk_fma_f32 v[58:59], v[58:59], 0.5, v[174:175] op_sel_hi:[1,0,1]
	v_pk_fma_f32 v[60:61], v[60:61], 0.5, v[176:177] op_sel_hi:[1,0,1]
	v_pk_fma_f32 v[66:67], v[66:67], 0.5, v[178:179] op_sel_hi:[1,0,1]
	v_pk_fma_f32 v[68:69], v[68:69], 0.5, v[180:181] op_sel_hi:[1,0,1]
	v_pk_add_f32 v[174:175], v[58:59], v[66:67]
	v_pk_add_f32 v[176:177], v[60:61], v[68:69]
	v_pk_mul_f32 v[178:179], v[58:59], v[58:59]
	v_pk_mul_f32 v[180:181], v[60:61], v[60:61]
	v_pk_fma_f32 v[178:179], v[66:67], v[66:67], v[178:179]
	v_pk_fma_f32 v[180:181], v[68:69], v[68:69], v[180:181]
	v_pk_add_f32 v[174:175], v[174:175], v[176:177]
	v_pk_add_f32 v[178:179], v[178:179], v[180:181]
	v_cvt_pk_bf16_f32 v130, v58, v59
	v_cvt_pk_bf16_f32 v131, v60, v61
	v_cvt_pk_bf16_f32 v132, v66, v67
	v_cvt_pk_bf16_f32 v133, v68, v69
	v_add_f32_e32 v174, v174, v175
	v_add_f32_e32 v178, v178, v179
	v_add_f32_e32 v139, v139, v174
	v_add_f32_e32 v197, v197, v178
	global_store_dwordx4 v135, v[118:121], s[18:19] offset:256
	global_store_dwordx4 v135, v[122:125], s[6:7] offset:256
	global_store_dwordx4 v135, v[126:129], s[8:9] offset:256
	global_store_dwordx4 v135, v[130:133], s[10:11] offset:256
	ds_bpermute_b32 v174, v201, v2
	ds_bpermute_b32 v175, v201, v4
	ds_bpermute_b32 v176, v201, v5
	ds_bpermute_b32 v177, v201, v139
	ds_bpermute_b32 v178, v201, v140
	ds_bpermute_b32 v179, v201, v186
	ds_bpermute_b32 v180, v201, v187
	ds_bpermute_b32 v181, v201, v197
	s_waitcnt lgkmcnt(0)
	v_add_f32_e32 v2, v2, v174
	v_add_f32_e32 v4, v4, v175
	v_add_f32_e32 v5, v5, v176
	v_add_f32_e32 v139, v139, v177
	v_add_f32_e32 v140, v140, v178
	v_add_f32_e32 v186, v186, v179
	v_add_f32_e32 v187, v187, v180
	v_add_f32_e32 v197, v197, v181
	ds_bpermute_b32 v174, v203, v2
	ds_bpermute_b32 v175, v203, v4
	ds_bpermute_b32 v176, v203, v5
	ds_bpermute_b32 v177, v203, v139
	ds_bpermute_b32 v178, v203, v140
	ds_bpermute_b32 v179, v203, v186
	ds_bpermute_b32 v180, v203, v187
	ds_bpermute_b32 v181, v203, v197
	s_waitcnt lgkmcnt(0)
	v_add_f32_e32 v2, v2, v174
	v_add_f32_e32 v4, v4, v175
	v_add_f32_e32 v5, v5, v176
	v_add_f32_e32 v139, v139, v177
	v_add_f32_e32 v140, v140, v178
	v_add_f32_e32 v186, v186, v179
	v_add_f32_e32 v187, v187, v180
	v_add_f32_e32 v197, v197, v181
	v_cmp_eq_u32_e32 vcc, 1, v191
	s_nop 1
	v_cndmask_b32_e32 v2, v2, v4, vcc
	v_cndmask_b32_e32 v140, v140, v186, vcc
	v_cmp_eq_u32_e32 vcc, 2, v191
	s_nop 1
	v_cndmask_b32_e32 v2, v2, v5, vcc
	v_cndmask_b32_e32 v140, v140, v187, vcc
	v_cmp_eq_u32_e32 vcc, 3, v191
	s_nop 1
	v_cndmask_b32_e32 v2, v2, v139, vcc
	v_cndmask_b32_e32 v140, v140, v197, vcc
	global_atomic_add_f32 v138, v2, s[16:17] offset:1024
	global_atomic_add_f32 v138, v140, s[16:17] offset:1028
	s_branch .LBB0_1106
.Lxfast:
	s_waitcnt lgkmcnt(0)
	s_cmp_lt_i32 s4, 32
	s_cselect_b32 s6, 0, 0xffffe000
	s_cselect_b32 s1, s56, s58
	s_cselect_b32 s0, s43, s57
	v_add_u32_e32 v187, s6, v180
	v_lshlrev_b32_e32 v187, 13, v187
	v_lshl_add_u32 v187, v178, 2, v187
	v_lshlrev_b32_e32 v226, 12, v180
	v_lshl_add_u32 v226, v178, 1, v226
	v_lshl_add_u32 v227, v191, 4, v180
	v_lshlrev_b32_e32 v227, 3, v227
	v_cmp_lt_i32_e32 vcc, v234, v230
	s_nop 1
	v_cndmask_b32_e32 v201, v228, v234, vcc
	v_cmp_lt_i32_e32 vcc, v195, v230
	s_nop 1
	v_cndmask_b32_e32 v203, v228, v195, vcc
	v_lshlrev_b32_e32 v201, 2, v201
	v_lshlrev_b32_e32 v203, 2, v203
	global_load_dwordx4 v[204:207], v187, s[0:1]
	global_load_dwordx4 v[142:145], v187, s[0:1] offset:16
	v_add_u32_e32 v197, 0x20000, v187
	global_load_dwordx4 v[208:211], v197, s[0:1]
	global_load_dwordx4 v[146:149], v197, s[0:1] offset:16
	v_add_u32_e32 v199, 0x40000, v187
	global_load_dwordx4 v[212:215], v199, s[0:1]
	global_load_dwordx4 v[150:153], v199, s[0:1] offset:16
	v_add_u32_e32 v197, 0x60000, v187
	global_load_dwordx4 v[216:219], v197, s[0:1]
	global_load_dwordx4 v[154:157], v197, s[0:1] offset:16
	global_load_dwordx4 v[158:161], v187, s[0:1] offset:512
	global_load_dwordx4 v[174:177], v187, s[0:1] offset:528
	v_add_u32_e32 v199, 0x20000, v187
	global_load_dwordx4 v[162:165], v199, s[0:1] offset:512
	global_load_dwordx4 v[178:181], v199, s[0:1] offset:528
	v_add_u32_e32 v197, 0x40000, v187
	global_load_dwordx4 v[166:169], v197, s[0:1] offset:512
	global_load_dwordx4 v[182:185], v197, s[0:1] offset:528
	v_add_u32_e32 v199, 0x60000, v187
	global_load_dwordx4 v[170:173], v199, s[0:1] offset:512
	global_load_dwordx4 v[222:225], v199, s[0:1] offset:528
	s_waitcnt vmcnt(14)
	v_pk_mul_f32 v[204:205], v[204:205], s[76:77] op_sel_hi:[1,0]
	v_pk_mul_f32 v[206:207], v[206:207], s[76:77] op_sel_hi:[1,0]
	v_pk_mul_f32 v[142:143], v[142:143], s[76:77] op_sel_hi:[1,0]
	v_pk_mul_f32 v[144:145], v[144:145], s[76:77] op_sel_hi:[1,0]
	v_pk_fma_f32 v[126:127], v[126:127], 0.5, v[204:205] op_sel_hi:[1,0,1]
	v_pk_fma_f32 v[128:129], v[128:129], 0.5, v[206:207] op_sel_hi:[1,0,1]
	v_pk_fma_f32 v[130:131], v[130:131], 0.5, v[142:143] op_sel_hi:[1,0,1]
	v_pk_fma_f32 v[132:133], v[132:133], 0.5, v[144:145] op_sel_hi:[1,0,1]
	v_pk_add_f32 v[204:205], v[126:127], v[130:131]
	v_pk_add_f32 v[206:207], v[128:129], v[132:133]
	v_pk_mul_f32 v[142:143], v[126:127], v[126:127]
	v_pk_mul_f32 v[144:145], v[128:129], v[128:129]
	v_pk_fma_f32 v[142:143], v[130:131], v[130:131], v[142:143]
	v_pk_fma_f32 v[144:145], v[132:133], v[132:133], v[144:145]
	v_pk_add_f32 v[204:205], v[204:205], v[206:207]
	v_pk_add_f32 v[142:143], v[142:143], v[144:145]
	v_add_f32_e32 v2, v204, v205
	v_add_f32_e32 v139, v142, v143
	v_cvt_pk_bf16_f32 v204, v126, v127
	v_cvt_pk_bf16_f32 v205, v128, v129
	v_cvt_pk_bf16_f32 v206, v130, v131
	v_cvt_pk_bf16_f32 v207, v132, v133
	s_waitcnt vmcnt(12)
	v_pk_mul_f32 v[208:209], v[208:209], s[76:77] op_sel_hi:[1,0]
	v_pk_mul_f32 v[210:211], v[210:211], s[76:77] op_sel_hi:[1,0]
	v_pk_mul_f32 v[146:147], v[146:147], s[76:77] op_sel_hi:[1,0]
	v_pk_mul_f32 v[148:149], v[148:149], s[76:77] op_sel_hi:[1,0]
	v_pk_fma_f32 v[118:119], v[118:119], 0.5, v[208:209] op_sel_hi:[1,0,1]
	v_pk_fma_f32 v[120:121], v[120:121], 0.5, v[210:211] op_sel_hi:[1,0,1]
	v_pk_fma_f32 v[122:123], v[122:123], 0.5, v[146:147] op_sel_hi:[1,0,1]
	v_pk_fma_f32 v[124:125], v[124:125], 0.5, v[148:149] op_sel_hi:[1,0,1]
	v_pk_add_f32 v[208:209], v[118:119], v[122:123]
	v_pk_add_f32 v[210:211], v[120:121], v[124:125]
	v_pk_mul_f32 v[146:147], v[118:119], v[118:119]
	v_pk_mul_f32 v[148:149], v[120:121], v[120:121]
	v_pk_fma_f32 v[146:147], v[122:123], v[122:123], v[146:147]
	v_pk_fma_f32 v[148:149], v[124:125], v[124:125], v[148:149]
	v_pk_add_f32 v[208:209], v[208:209], v[210:211]
	v_pk_add_f32 v[146:147], v[146:147], v[148:149]
	v_add_f32_e32 v4, v208, v209
	v_add_f32_e32 v140, v146, v147
	v_cvt_pk_bf16_f32 v208, v118, v119
	v_cvt_pk_bf16_f32 v209, v120, v121
	v_cvt_pk_bf16_f32 v210, v122, v123
	v_cvt_pk_bf16_f32 v211, v124, v125
	s_waitcnt vmcnt(10)
	v_pk_mul_f32 v[212:213], v[212:213], s[76:77] op_sel_hi:[1,0]
	v_pk_mul_f32 v[214:215], v[214:215], s[76:77] op_sel_hi:[1,0]
	v_pk_mul_f32 v[150:151], v[150:151], s[76:77] op_sel_hi:[1,0]
	v_pk_mul_f32 v[152:153], v[152:153], s[76:77] op_sel_hi:[1,0]
	v_pk_fma_f32 v[110:111], v[110:111], 0.5, v[212:213] op_sel_hi:[1,0,1]
	v_pk_fma_f32 v[112:113], v[112:113], 0.5, v[214:215] op_sel_hi:[1,0,1]
	v_pk_fma_f32 v[114:115], v[114:115], 0.5, v[150:151] op_sel_hi:[1,0,1]
	v_pk_fma_f32 v[116:117], v[116:117], 0.5, v[152:153] op_sel_hi:[1,0,1]
	v_pk_add_f32 v[212:213], v[110:111], v[114:115]
	v_pk_add_f32 v[214:215], v[112:113], v[116:117]
	v_pk_mul_f32 v[150:151], v[110:111], v[110:111]
	v_pk_mul_f32 v[152:153], v[112:113], v[112:113]
	v_pk_fma_f32 v[150:151], v[114:115], v[114:115], v[150:151]
	v_pk_fma_f32 v[152:153], v[116:117], v[116:117], v[152:153]
	v_pk_add_f32 v[212:213], v[212:213], v[214:215]
	v_pk_add_f32 v[150:151], v[150:151], v[152:153]
	v_add_f32_e32 v5, v212, v213
	v_add_f32_e32 v141, v150, v151
	v_cvt_pk_bf16_f32 v212, v110, v111
	v_cvt_pk_bf16_f32 v213, v112, v113
	v_cvt_pk_bf16_f32 v214, v114, v115
	v_cvt_pk_bf16_f32 v215, v116, v117
	s_waitcnt vmcnt(8)
	v_pk_mul_f32 v[216:217], v[216:217], s[76:77] op_sel_hi:[1,0]
	v_pk_mul_f32 v[218:219], v[218:219], s[76:77] op_sel_hi:[1,0]
	v_pk_mul_f32 v[154:155], v[154:155], s[76:77] op_sel_hi:[1,0]
	v_pk_mul_f32 v[156:157], v[156:157], s[76:77] op_sel_hi:[1,0]
	v_pk_fma_f32 v[102:103], v[102:103], 0.5, v[216:217] op_sel_hi:[1,0,1]
	v_pk_fma_f32 v[104:105], v[104:105], 0.5, v[218:219] op_sel_hi:[1,0,1]
	v_pk_fma_f32 v[106:107], v[106:107], 0.5, v[154:155] op_sel_hi:[1,0,1]
	v_pk_fma_f32 v[108:109], v[108:109], 0.5, v[156:157] op_sel_hi:[1,0,1]
	v_pk_add_f32 v[216:217], v[102:103], v[106:107]
	v_pk_add_f32 v[218:219], v[104:105], v[108:109]
	v_pk_mul_f32 v[154:155], v[102:103], v[102:103]
	v_pk_mul_f32 v[156:157], v[104:105], v[104:105]
	v_pk_fma_f32 v[154:155], v[106:107], v[106:107], v[154:155]
	v_pk_fma_f32 v[156:157], v[108:109], v[108:109], v[156:157]
	v_pk_add_f32 v[216:217], v[216:217], v[218:219]
	v_pk_add_f32 v[154:155], v[154:155], v[156:157]
	v_add_f32_e32 v138, v216, v217
	v_add_f32_e32 v186, v154, v155
	v_cvt_pk_bf16_f32 v216, v102, v103
	v_cvt_pk_bf16_f32 v217, v104, v105
	v_cvt_pk_bf16_f32 v218, v106, v107
	v_cvt_pk_bf16_f32 v219, v108, v109
	v_add_u32_e32 v197, 0x100000, v187
	global_load_dwordx4 v[102:105], v197, s[0:1]
	global_load_dwordx4 v[118:121], v197, s[0:1] offset:16
	v_add_u32_e32 v199, 0x120000, v187
	global_load_dwordx4 v[106:109], v199, s[0:1]
	global_load_dwordx4 v[122:125], v199, s[0:1] offset:16
	v_add_u32_e32 v197, 0x140000, v187
	global_load_dwordx4 v[110:113], v197, s[0:1]
	global_load_dwordx4 v[126:129], v197, s[0:1] offset:16
	v_add_u32_e32 v199, 0x160000, v187
	global_load_dwordx4 v[114:117], v199, s[0:1]
	global_load_dwordx4 v[130:133], v199, s[0:1] offset:16
	global_store_dwordx4 v226, v[204:207], s[18:19]
	v_add_u32_e32 v197, 0x10000, v226
	global_store_dwordx4 v197, v[208:211], s[18:19]
	v_add_u32_e32 v199, 0x20000, v226
	global_store_dwordx4 v199, v[212:215], s[18:19]
	v_add_u32_e32 v197, 0x30000, v226
	global_store_dwordx4 v197, v[216:219], s[18:19]
	s_waitcnt vmcnt(18)
	v_pk_mul_f32 v[158:159], v[158:159], s[76:77] op_sel_hi:[1,0]
	v_pk_mul_f32 v[160:161], v[160:161], s[76:77] op_sel_hi:[1,0]
	v_pk_mul_f32 v[174:175], v[174:175], s[76:77] op_sel_hi:[1,0]
	v_pk_mul_f32 v[176:177], v[176:177], s[76:77] op_sel_hi:[1,0]
	v_pk_fma_f32 v[94:95], v[94:95], 0.5, v[158:159] op_sel_hi:[1,0,1]
	v_pk_fma_f32 v[96:97], v[96:97], 0.5, v[160:161] op_sel_hi:[1,0,1]
	v_pk_fma_f32 v[98:99], v[98:99], 0.5, v[174:175] op_sel_hi:[1,0,1]
	v_pk_fma_f32 v[100:101], v[100:101], 0.5, v[176:177] op_sel_hi:[1,0,1]
	v_pk_add_f32 v[158:159], v[94:95], v[98:99]
	v_pk_add_f32 v[160:161], v[96:97], v[100:101]
	v_pk_mul_f32 v[174:175], v[94:95], v[94:95]
	v_pk_mul_f32 v[176:177], v[96:97], v[96:97]
	v_pk_fma_f32 v[174:175], v[98:99], v[98:99], v[174:175]
	v_pk_fma_f32 v[176:177], v[100:101], v[100:101], v[176:177]
	v_pk_add_f32 v[158:159], v[158:159], v[160:161]
	v_pk_add_f32 v[174:175], v[174:175], v[176:177]
	v_add_f32_e32 v158, v158, v159
	v_add_f32_e32 v174, v174, v175
	v_add_f32_e32 v2, v2, v158
	v_add_f32_e32 v139, v139, v174
	v_cvt_pk_bf16_f32 v158, v94, v95
	v_cvt_pk_bf16_f32 v159, v96, v97
	v_cvt_pk_bf16_f32 v160, v98, v99
	v_cvt_pk_bf16_f32 v161, v100, v101
	s_waitcnt vmcnt(16)
	v_pk_mul_f32 v[162:163], v[162:163], s[76:77] op_sel_hi:[1,0]
	v_pk_mul_f32 v[164:165], v[164:165], s[76:77] op_sel_hi:[1,0]
	v_pk_mul_f32 v[178:179], v[178:179], s[76:77] op_sel_hi:[1,0]
	v_pk_mul_f32 v[180:181], v[180:181], s[76:77] op_sel_hi:[1,0]
	v_pk_fma_f32 v[86:87], v[86:87], 0.5, v[162:163] op_sel_hi:[1,0,1]
	v_pk_fma_f32 v[88:89], v[88:89], 0.5, v[164:165] op_sel_hi:[1,0,1]
	v_pk_fma_f32 v[90:91], v[90:91], 0.5, v[178:179] op_sel_hi:[1,0,1]
	v_pk_fma_f32 v[92:93], v[92:93], 0.5, v[180:181] op_sel_hi:[1,0,1]
	v_pk_add_f32 v[162:163], v[86:87], v[90:91]
	v_pk_add_f32 v[164:165], v[88:89], v[92:93]
	v_pk_mul_f32 v[178:179], v[86:87], v[86:87]
	v_pk_mul_f32 v[180:181], v[88:89], v[88:89]
	v_pk_fma_f32 v[178:179], v[90:91], v[90:91], v[178:179]
	v_pk_fma_f32 v[180:181], v[92:93], v[92:93], v[180:181]
	v_pk_add_f32 v[162:163], v[162:163], v[164:165]
	v_pk_add_f32 v[178:179], v[178:179], v[180:181]
	v_add_f32_e32 v162, v162, v163
	v_add_f32_e32 v178, v178, v179
	v_add_f32_e32 v4, v4, v162
	v_add_f32_e32 v140, v140, v178
	v_cvt_pk_bf16_f32 v162, v86, v87
	v_cvt_pk_bf16_f32 v163, v88, v89
	v_cvt_pk_bf16_f32 v164, v90, v91
	v_cvt_pk_bf16_f32 v165, v92, v93
	s_waitcnt vmcnt(14)
	v_pk_mul_f32 v[166:167], v[166:167], s[76:77] op_sel_hi:[1,0]
	v_pk_mul_f32 v[168:169], v[168:169], s[76:77] op_sel_hi:[1,0]
	v_pk_mul_f32 v[182:183], v[182:183], s[76:77] op_sel_hi:[1,0]
	v_pk_mul_f32 v[184:185], v[184:185], s[76:77] op_sel_hi:[1,0]
	v_pk_fma_f32 v[78:79], v[78:79], 0.5, v[166:167] op_sel_hi:[1,0,1]
	v_pk_fma_f32 v[80:81], v[80:81], 0.5, v[168:169] op_sel_hi:[1,0,1]
	v_pk_fma_f32 v[82:83], v[82:83], 0.5, v[182:183] op_sel_hi:[1,0,1]
	v_pk_fma_f32 v[84:85], v[84:85], 0.5, v[184:185] op_sel_hi:[1,0,1]
	v_pk_add_f32 v[166:167], v[78:79], v[82:83]
	v_pk_add_f32 v[168:169], v[80:81], v[84:85]
	v_pk_mul_f32 v[182:183], v[78:79], v[78:79]
	v_pk_mul_f32 v[184:185], v[80:81], v[80:81]
	v_pk_fma_f32 v[182:183], v[82:83], v[82:83], v[182:183]
	v_pk_fma_f32 v[184:185], v[84:85], v[84:85], v[184:185]
	v_pk_add_f32 v[166:167], v[166:167], v[168:169]
	v_pk_add_f32 v[182:183], v[182:183], v[184:185]
	v_add_f32_e32 v166, v166, v167
	v_add_f32_e32 v182, v182, v183
	v_add_f32_e32 v5, v5, v166
	v_add_f32_e32 v141, v141, v182
	v_cvt_pk_bf16_f32 v166, v78, v79
	v_cvt_pk_bf16_f32 v167, v80, v81
	v_cvt_pk_bf16_f32 v168, v82, v83
	v_cvt_pk_bf16_f32 v169, v84, v85
	s_waitcnt vmcnt(12)
	v_pk_mul_f32 v[170:171], v[170:171], s[76:77] op_sel_hi:[1,0]
	v_pk_mul_f32 v[172:173], v[172:173], s[76:77] op_sel_hi:[1,0]
	v_pk_mul_f32 v[222:223], v[222:223], s[76:77] op_sel_hi:[1,0]
	v_pk_mul_f32 v[224:225], v[224:225], s[76:77] op_sel_hi:[1,0]
	v_pk_fma_f32 v[70:71], v[70:71], 0.5, v[170:171] op_sel_hi:[1,0,1]
	v_pk_fma_f32 v[72:73], v[72:73], 0.5, v[172:173] op_sel_hi:[1,0,1]
	v_pk_fma_f32 v[74:75], v[74:75], 0.5, v[222:223] op_sel_hi:[1,0,1]
	v_pk_fma_f32 v[76:77], v[76:77], 0.5, v[224:225] op_sel_hi:[1,0,1]
	v_pk_add_f32 v[170:171], v[70:71], v[74:75]
	v_pk_add_f32 v[172:173], v[72:73], v[76:77]
	v_pk_mul_f32 v[222:223], v[70:71], v[70:71]
	v_pk_mul_f32 v[224:225], v[72:73], v[72:73]
	v_pk_fma_f32 v[222:223], v[74:75], v[74:75], v[222:223]
	v_pk_fma_f32 v[224:225], v[76:77], v[76:77], v[224:225]
	v_pk_add_f32 v[170:171], v[170:171], v[172:173]
	v_pk_add_f32 v[222:223], v[222:223], v[224:225]
	v_add_f32_e32 v170, v170, v171
	v_add_f32_e32 v222, v222, v223
	v_add_f32_e32 v138, v138, v170
	v_add_f32_e32 v186, v186, v222
	v_cvt_pk_bf16_f32 v170, v70, v71
	v_cvt_pk_bf16_f32 v171, v72, v73
	v_cvt_pk_bf16_f32 v172, v74, v75
	v_cvt_pk_bf16_f32 v173, v76, v77
	v_add_u32_e32 v199, 0x100000, v187
	global_load_dwordx4 v[70:73], v199, s[0:1] offset:512
	global_load_dwordx4 v[86:89], v199, s[0:1] offset:528
	v_add_u32_e32 v197, 0x120000, v187
	global_load_dwordx4 v[74:77], v197, s[0:1] offset:512
	global_load_dwordx4 v[90:93], v197, s[0:1] offset:528
	v_add_u32_e32 v199, 0x140000, v187
	global_load_dwordx4 v[78:81], v199, s[0:1] offset:512
	global_load_dwordx4 v[94:97], v199, s[0:1] offset:528
	v_add_u32_e32 v197, 0x160000, v187
	global_load_dwordx4 v[82:85], v197, s[0:1] offset:512
	global_load_dwordx4 v[98:101], v197, s[0:1] offset:528
	global_store_dwordx4 v226, v[158:161], s[18:19] offset:256
	v_add_u32_e32 v199, 0x10000, v226
	global_store_dwordx4 v199, v[162:165], s[18:19] offset:256
	v_add_u32_e32 v197, 0x20000, v226
	global_store_dwordx4 v197, v[166:169], s[18:19] offset:256
	v_add_u32_e32 v199, 0x30000, v226
	global_store_dwordx4 v199, v[170:173], s[18:19] offset:256
	ds_bpermute_b32 v134, v201, v2
	ds_bpermute_b32 v135, v201, v4
	ds_bpermute_b32 v136, v201, v5
	ds_bpermute_b32 v137, v201, v138
	ds_bpermute_b32 v222, v201, v139
	ds_bpermute_b32 v223, v201, v140
	ds_bpermute_b32 v224, v201, v141
	ds_bpermute_b32 v225, v201, v186
	s_waitcnt lgkmcnt(0)
	v_add_f32_e32 v2, v2, v134
	v_add_f32_e32 v4, v4, v135
	v_add_f32_e32 v5, v5, v136
	v_add_f32_e32 v138, v138, v137
	v_add_f32_e32 v139, v139, v222
	v_add_f32_e32 v140, v140, v223
	v_add_f32_e32 v141, v141, v224
	v_add_f32_e32 v186, v186, v225
	ds_bpermute_b32 v134, v203, v2
	ds_bpermute_b32 v135, v203, v4
	ds_bpermute_b32 v136, v203, v5
	ds_bpermute_b32 v137, v203, v138
	ds_bpermute_b32 v222, v203, v139
	ds_bpermute_b32 v223, v203, v140
	ds_bpermute_b32 v224, v203, v141
	ds_bpermute_b32 v225, v203, v186
	s_waitcnt lgkmcnt(0)
	v_add_f32_e32 v2, v2, v134
	v_add_f32_e32 v4, v4, v135
	v_add_f32_e32 v5, v5, v136
	v_add_f32_e32 v138, v138, v137
	v_add_f32_e32 v139, v139, v222
	v_add_f32_e32 v140, v140, v223
	v_add_f32_e32 v141, v141, v224
	v_add_f32_e32 v186, v186, v225
	v_cmp_eq_u32_e32 vcc, 1, v191
	s_nop 1
	v_cndmask_b32_e32 v2, v2, v4, vcc
	v_cndmask_b32_e32 v139, v139, v140, vcc
	v_cmp_eq_u32_e32 vcc, 2, v191
	s_nop 1
	v_cndmask_b32_e32 v2, v2, v5, vcc
	v_cndmask_b32_e32 v139, v139, v141, vcc
	v_cmp_eq_u32_e32 vcc, 3, v191
	s_nop 1
	v_cndmask_b32_e32 v2, v2, v138, vcc
	v_cndmask_b32_e32 v139, v139, v186, vcc
	global_atomic_add_f32 v227, v2, s[16:17]
	global_atomic_add_f32 v227, v139, s[16:17] offset:4
	s_waitcnt vmcnt(24)
	v_pk_mul_f32 v[102:103], v[102:103], s[76:77] op_sel_hi:[1,0]
	v_pk_mul_f32 v[104:105], v[104:105], s[76:77] op_sel_hi:[1,0]
	v_pk_mul_f32 v[118:119], v[118:119], s[76:77] op_sel_hi:[1,0]
	v_pk_mul_f32 v[120:121], v[120:121], s[76:77] op_sel_hi:[1,0]
	v_pk_fma_f32 v[46:47], v[46:47], 0.5, v[102:103] op_sel_hi:[1,0,1]
	v_pk_fma_f32 v[48:49], v[48:49], 0.5, v[104:105] op_sel_hi:[1,0,1]
	v_pk_fma_f32 v[50:51], v[50:51], 0.5, v[118:119] op_sel_hi:[1,0,1]
	v_pk_fma_f32 v[52:53], v[52:53], 0.5, v[120:121] op_sel_hi:[1,0,1]
	v_pk_add_f32 v[102:103], v[46:47], v[50:51]
	v_pk_add_f32 v[104:105], v[48:49], v[52:53]
	v_pk_mul_f32 v[118:119], v[46:47], v[46:47]
	v_pk_mul_f32 v[120:121], v[48:49], v[48:49]
	v_pk_fma_f32 v[118:119], v[50:51], v[50:51], v[118:119]
	v_pk_fma_f32 v[120:121], v[52:53], v[52:53], v[120:121]
	v_pk_add_f32 v[102:103], v[102:103], v[104:105]
	v_pk_add_f32 v[118:119], v[118:119], v[120:121]
	v_add_f32_e32 v2, v102, v103
	v_add_f32_e32 v139, v118, v119
	v_cvt_pk_bf16_f32 v102, v46, v47
	v_cvt_pk_bf16_f32 v103, v48, v49
	v_cvt_pk_bf16_f32 v104, v50, v51
	v_cvt_pk_bf16_f32 v105, v52, v53
	s_waitcnt vmcnt(22)
	v_pk_mul_f32 v[106:107], v[106:107], s[76:77] op_sel_hi:[1,0]
	v_pk_mul_f32 v[108:109], v[108:109], s[76:77] op_sel_hi:[1,0]
	v_pk_mul_f32 v[122:123], v[122:123], s[76:77] op_sel_hi:[1,0]
	v_pk_mul_f32 v[124:125], v[124:125], s[76:77] op_sel_hi:[1,0]
	v_pk_fma_f32 v[38:39], v[38:39], 0.5, v[106:107] op_sel_hi:[1,0,1]
	v_pk_fma_f32 v[40:41], v[40:41], 0.5, v[108:109] op_sel_hi:[1,0,1]
	v_pk_fma_f32 v[42:43], v[42:43], 0.5, v[122:123] op_sel_hi:[1,0,1]
	v_pk_fma_f32 v[44:45], v[44:45], 0.5, v[124:125] op_sel_hi:[1,0,1]
	v_pk_add_f32 v[106:107], v[38:39], v[42:43]
	v_pk_add_f32 v[108:109], v[40:41], v[44:45]
	v_pk_mul_f32 v[122:123], v[38:39], v[38:39]
	v_pk_mul_f32 v[124:125], v[40:41], v[40:41]
	v_pk_fma_f32 v[122:123], v[42:43], v[42:43], v[122:123]
	v_pk_fma_f32 v[124:125], v[44:45], v[44:45], v[124:125]
	v_pk_add_f32 v[106:107], v[106:107], v[108:109]
	v_pk_add_f32 v[122:123], v[122:123], v[124:125]
	v_add_f32_e32 v4, v106, v107
	v_add_f32_e32 v140, v122, v123
	v_cvt_pk_bf16_f32 v106, v38, v39
	v_cvt_pk_bf16_f32 v107, v40, v41
	v_cvt_pk_bf16_f32 v108, v42, v43
	v_cvt_pk_bf16_f32 v109, v44, v45
	s_waitcnt vmcnt(20)
	v_pk_mul_f32 v[110:111], v[110:111], s[76:77] op_sel_hi:[1,0]
	v_pk_mul_f32 v[112:113], v[112:113], s[76:77] op_sel_hi:[1,0]
	v_pk_mul_f32 v[126:127], v[126:127], s[76:77] op_sel_hi:[1,0]
	v_pk_mul_f32 v[128:129], v[128:129], s[76:77] op_sel_hi:[1,0]
	v_pk_fma_f32 v[30:31], v[30:31], 0.5, v[110:111] op_sel_hi:[1,0,1]
	v_pk_fma_f32 v[32:33], v[32:33], 0.5, v[112:113] op_sel_hi:[1,0,1]
	v_pk_fma_f32 v[34:35], v[34:35], 0.5, v[126:127] op_sel_hi:[1,0,1]
	v_pk_fma_f32 v[36:37], v[36:37], 0.5, v[128:129] op_sel_hi:[1,0,1]
	v_pk_add_f32 v[110:111], v[30:31], v[34:35]
	v_pk_add_f32 v[112:113], v[32:33], v[36:37]
	v_pk_mul_f32 v[126:127], v[30:31], v[30:31]
	v_pk_mul_f32 v[128:129], v[32:33], v[32:33]
	v_pk_fma_f32 v[126:127], v[34:35], v[34:35], v[126:127]
	v_pk_fma_f32 v[128:129], v[36:37], v[36:37], v[128:129]
	v_pk_add_f32 v[110:111], v[110:111], v[112:113]
	v_pk_add_f32 v[126:127], v[126:127], v[128:129]
	v_add_f32_e32 v5, v110, v111
	v_add_f32_e32 v141, v126, v127
	v_cvt_pk_bf16_f32 v110, v30, v31
	v_cvt_pk_bf16_f32 v111, v32, v33
	v_cvt_pk_bf16_f32 v112, v34, v35
	v_cvt_pk_bf16_f32 v113, v36, v37
	s_waitcnt vmcnt(18)
	v_pk_mul_f32 v[114:115], v[114:115], s[76:77] op_sel_hi:[1,0]
	v_pk_mul_f32 v[116:117], v[116:117], s[76:77] op_sel_hi:[1,0]
	v_pk_mul_f32 v[130:131], v[130:131], s[76:77] op_sel_hi:[1,0]
	v_pk_mul_f32 v[132:133], v[132:133], s[76:77] op_sel_hi:[1,0]
	v_pk_fma_f32 v[22:23], v[22:23], 0.5, v[114:115] op_sel_hi:[1,0,1]
	v_pk_fma_f32 v[24:25], v[24:25], 0.5, v[116:117] op_sel_hi:[1,0,1]
	v_pk_fma_f32 v[26:27], v[26:27], 0.5, v[130:131] op_sel_hi:[1,0,1]
	v_pk_fma_f32 v[28:29], v[28:29], 0.5, v[132:133] op_sel_hi:[1,0,1]
	v_pk_add_f32 v[114:115], v[22:23], v[26:27]
	v_pk_add_f32 v[116:117], v[24:25], v[28:29]
	v_pk_mul_f32 v[130:131], v[22:23], v[22:23]
	v_pk_mul_f32 v[132:133], v[24:25], v[24:25]
	v_pk_fma_f32 v[130:131], v[26:27], v[26:27], v[130:131]
	v_pk_fma_f32 v[132:133], v[28:29], v[28:29], v[132:133]
	v_pk_add_f32 v[114:115], v[114:115], v[116:117]
	v_pk_add_f32 v[130:131], v[130:131], v[132:133]
	v_add_f32_e32 v138, v114, v115
	v_add_f32_e32 v186, v130, v131
	v_cvt_pk_bf16_f32 v114, v22, v23
	v_cvt_pk_bf16_f32 v115, v24, v25
	v_cvt_pk_bf16_f32 v116, v26, v27
	v_cvt_pk_bf16_f32 v117, v28, v29
	v_add_u32_e32 v197, 0x80000, v226
	global_store_dwordx4 v197, v[102:105], s[18:19]
	v_add_u32_e32 v199, 0x90000, v226
	global_store_dwordx4 v199, v[106:109], s[18:19]
	v_add_u32_e32 v197, 0xa0000, v226
	global_store_dwordx4 v197, v[110:113], s[18:19]
	v_add_u32_e32 v199, 0xb0000, v226
	global_store_dwordx4 v199, v[114:117], s[18:19]
	s_waitcnt vmcnt(16)
	v_pk_mul_f32 v[70:71], v[70:71], s[76:77] op_sel_hi:[1,0]
	v_pk_mul_f32 v[72:73], v[72:73], s[76:77] op_sel_hi:[1,0]
	v_pk_mul_f32 v[86:87], v[86:87], s[76:77] op_sel_hi:[1,0]
	v_pk_mul_f32 v[88:89], v[88:89], s[76:77] op_sel_hi:[1,0]
	v_pk_fma_f32 v[14:15], v[14:15], 0.5, v[70:71] op_sel_hi:[1,0,1]
	v_pk_fma_f32 v[16:17], v[16:17], 0.5, v[72:73] op_sel_hi:[1,0,1]
	v_pk_fma_f32 v[18:19], v[18:19], 0.5, v[86:87] op_sel_hi:[1,0,1]
	v_pk_fma_f32 v[20:21], v[20:21], 0.5, v[88:89] op_sel_hi:[1,0,1]
	v_pk_add_f32 v[70:71], v[14:15], v[18:19]
	v_pk_add_f32 v[72:73], v[16:17], v[20:21]
	v_pk_mul_f32 v[86:87], v[14:15], v[14:15]
	v_pk_mul_f32 v[88:89], v[16:17], v[16:17]
	v_pk_fma_f32 v[86:87], v[18:19], v[18:19], v[86:87]
	v_pk_fma_f32 v[88:89], v[20:21], v[20:21], v[88:89]
	v_pk_add_f32 v[70:71], v[70:71], v[72:73]
	v_pk_add_f32 v[86:87], v[86:87], v[88:89]
	v_add_f32_e32 v70, v70, v71
	v_add_f32_e32 v86, v86, v87
	v_add_f32_e32 v2, v2, v70
	v_add_f32_e32 v139, v139, v86
	v_cvt_pk_bf16_f32 v70, v14, v15
	v_cvt_pk_bf16_f32 v71, v16, v17
	v_cvt_pk_bf16_f32 v72, v18, v19
	v_cvt_pk_bf16_f32 v73, v20, v21
	s_waitcnt vmcnt(14)
	v_pk_mul_f32 v[74:75], v[74:75], s[76:77] op_sel_hi:[1,0]
	v_pk_mul_f32 v[76:77], v[76:77], s[76:77] op_sel_hi:[1,0]
	v_pk_mul_f32 v[90:91], v[90:91], s[76:77] op_sel_hi:[1,0]
	v_pk_mul_f32 v[92:93], v[92:93], s[76:77] op_sel_hi:[1,0]
	v_pk_fma_f32 v[6:7], v[6:7], 0.5, v[74:75] op_sel_hi:[1,0,1]
	v_pk_fma_f32 v[8:9], v[8:9], 0.5, v[76:77] op_sel_hi:[1,0,1]
	v_pk_fma_f32 v[10:11], v[10:11], 0.5, v[90:91] op_sel_hi:[1,0,1]
	v_pk_fma_f32 v[12:13], v[12:13], 0.5, v[92:93] op_sel_hi:[1,0,1]
	v_pk_add_f32 v[74:75], v[6:7], v[10:11]
	v_pk_add_f32 v[76:77], v[8:9], v[12:13]
	v_pk_mul_f32 v[90:91], v[6:7], v[6:7]
	v_pk_mul_f32 v[92:93], v[8:9], v[8:9]
	v_pk_fma_f32 v[90:91], v[10:11], v[10:11], v[90:91]
	v_pk_fma_f32 v[92:93], v[12:13], v[12:13], v[92:93]
	v_pk_add_f32 v[74:75], v[74:75], v[76:77]
	v_pk_add_f32 v[90:91], v[90:91], v[92:93]
	v_add_f32_e32 v74, v74, v75
	v_add_f32_e32 v90, v90, v91
	v_add_f32_e32 v4, v4, v74
	v_add_f32_e32 v140, v140, v90
	v_cvt_pk_bf16_f32 v74, v6, v7
	v_cvt_pk_bf16_f32 v75, v8, v9
	v_cvt_pk_bf16_f32 v76, v10, v11
	v_cvt_pk_bf16_f32 v77, v12, v13
	s_waitcnt vmcnt(12)
	v_pk_mul_f32 v[78:79], v[78:79], s[76:77] op_sel_hi:[1,0]
	v_pk_mul_f32 v[80:81], v[80:81], s[76:77] op_sel_hi:[1,0]
	v_pk_mul_f32 v[94:95], v[94:95], s[76:77] op_sel_hi:[1,0]
	v_pk_mul_f32 v[96:97], v[96:97], s[76:77] op_sel_hi:[1,0]
	v_pk_fma_f32 v[54:55], v[54:55], 0.5, v[78:79] op_sel_hi:[1,0,1]
	v_pk_fma_f32 v[56:57], v[56:57], 0.5, v[80:81] op_sel_hi:[1,0,1]
	v_pk_fma_f32 v[62:63], v[62:63], 0.5, v[94:95] op_sel_hi:[1,0,1]
	v_pk_fma_f32 v[64:65], v[64:65], 0.5, v[96:97] op_sel_hi:[1,0,1]
	v_pk_add_f32 v[78:79], v[54:55], v[62:63]
	v_pk_add_f32 v[80:81], v[56:57], v[64:65]
	v_pk_mul_f32 v[94:95], v[54:55], v[54:55]
	v_pk_mul_f32 v[96:97], v[56:57], v[56:57]
	v_pk_fma_f32 v[94:95], v[62:63], v[62:63], v[94:95]
	v_pk_fma_f32 v[96:97], v[64:65], v[64:65], v[96:97]
	v_pk_add_f32 v[78:79], v[78:79], v[80:81]
	v_pk_add_f32 v[94:95], v[94:95], v[96:97]
	v_add_f32_e32 v78, v78, v79
	v_add_f32_e32 v94, v94, v95
	v_add_f32_e32 v5, v5, v78
	v_add_f32_e32 v141, v141, v94
	v_cvt_pk_bf16_f32 v78, v54, v55
	v_cvt_pk_bf16_f32 v79, v56, v57
	v_cvt_pk_bf16_f32 v80, v62, v63
	v_cvt_pk_bf16_f32 v81, v64, v65
	s_waitcnt vmcnt(10)
	v_pk_mul_f32 v[82:83], v[82:83], s[76:77] op_sel_hi:[1,0]
	v_pk_mul_f32 v[84:85], v[84:85], s[76:77] op_sel_hi:[1,0]
	v_pk_mul_f32 v[98:99], v[98:99], s[76:77] op_sel_hi:[1,0]
	v_pk_mul_f32 v[100:101], v[100:101], s[76:77] op_sel_hi:[1,0]
	v_pk_fma_f32 v[58:59], v[58:59], 0.5, v[82:83] op_sel_hi:[1,0,1]
	v_pk_fma_f32 v[60:61], v[60:61], 0.5, v[84:85] op_sel_hi:[1,0,1]
	v_pk_fma_f32 v[66:67], v[66:67], 0.5, v[98:99] op_sel_hi:[1,0,1]
	v_pk_fma_f32 v[68:69], v[68:69], 0.5, v[100:101] op_sel_hi:[1,0,1]
	v_pk_add_f32 v[82:83], v[58:59], v[66:67]
	v_pk_add_f32 v[84:85], v[60:61], v[68:69]
	v_pk_mul_f32 v[98:99], v[58:59], v[58:59]
	v_pk_mul_f32 v[100:101], v[60:61], v[60:61]
	v_pk_fma_f32 v[98:99], v[66:67], v[66:67], v[98:99]
	v_pk_fma_f32 v[100:101], v[68:69], v[68:69], v[100:101]
	v_pk_add_f32 v[82:83], v[82:83], v[84:85]
	v_pk_add_f32 v[98:99], v[98:99], v[100:101]
	v_add_f32_e32 v82, v82, v83
	v_add_f32_e32 v98, v98, v99
	v_add_f32_e32 v138, v138, v82
	v_add_f32_e32 v186, v186, v98
	v_cvt_pk_bf16_f32 v82, v58, v59
	v_cvt_pk_bf16_f32 v83, v60, v61
	v_cvt_pk_bf16_f32 v84, v66, v67
	v_cvt_pk_bf16_f32 v85, v68, v69
	v_add_u32_e32 v197, 0x80000, v226
	global_store_dwordx4 v197, v[70:73], s[18:19] offset:256
	v_add_u32_e32 v199, 0x90000, v226
	global_store_dwordx4 v199, v[74:77], s[18:19] offset:256
	v_add_u32_e32 v197, 0xa0000, v226
	global_store_dwordx4 v197, v[78:81], s[18:19] offset:256
	v_add_u32_e32 v199, 0xb0000, v226
	global_store_dwordx4 v199, v[82:85], s[18:19] offset:256
	ds_bpermute_b32 v134, v201, v2
	ds_bpermute_b32 v135, v201, v4
	ds_bpermute_b32 v136, v201, v5
	ds_bpermute_b32 v137, v201, v138
	ds_bpermute_b32 v98, v201, v139
	ds_bpermute_b32 v99, v201, v140
	ds_bpermute_b32 v100, v201, v141
	ds_bpermute_b32 v101, v201, v186
	s_waitcnt lgkmcnt(0)
	v_add_f32_e32 v2, v2, v134
	v_add_f32_e32 v4, v4, v135
	v_add_f32_e32 v5, v5, v136
	v_add_f32_e32 v138, v138, v137
	v_add_f32_e32 v139, v139, v98
	v_add_f32_e32 v140, v140, v99
	v_add_f32_e32 v141, v141, v100
	v_add_f32_e32 v186, v186, v101
	ds_bpermute_b32 v134, v203, v2
	ds_bpermute_b32 v135, v203, v4
	ds_bpermute_b32 v136, v203, v5
	ds_bpermute_b32 v137, v203, v138
	ds_bpermute_b32 v98, v203, v139
	ds_bpermute_b32 v99, v203, v140
	ds_bpermute_b32 v100, v203, v141
	ds_bpermute_b32 v101, v203, v186
	s_waitcnt lgkmcnt(0)
	v_add_f32_e32 v2, v2, v134
	v_add_f32_e32 v4, v4, v135
	v_add_f32_e32 v5, v5, v136
	v_add_f32_e32 v138, v138, v137
	v_add_f32_e32 v139, v139, v98
	v_add_f32_e32 v140, v140, v99
	v_add_f32_e32 v141, v141, v100
	v_add_f32_e32 v186, v186, v101
	v_cmp_eq_u32_e32 vcc, 1, v191
	s_nop 1
	v_cndmask_b32_e32 v2, v2, v4, vcc
	v_cndmask_b32_e32 v139, v139, v140, vcc
	v_cmp_eq_u32_e32 vcc, 2, v191
	s_nop 1
	v_cndmask_b32_e32 v2, v2, v5, vcc
	v_cndmask_b32_e32 v139, v139, v141, vcc
	v_cmp_eq_u32_e32 vcc, 3, v191
	s_nop 1
	v_cndmask_b32_e32 v2, v2, v138, vcc
	v_cndmask_b32_e32 v139, v139, v186, vcc
	global_atomic_add_f32 v227, v2, s[16:17] offset:1024
	global_atomic_add_f32 v227, v139, s[16:17] offset:1028
	s_branch .LBB0_1106

.Lrfast_wo:
	v_lshlrev_b32_e32 v134, 12, v180
	v_lshl_add_u32 v134, v178, 1, v134
	v_add_u32_e32 v135, 0x80000, v134
	v_lshl_add_u32 v138, v191, 4, v180
	v_lshlrev_b32_e32 v138, 3, v138
	s_add_u32 s6, s16, 0x10000
	s_addc_u32 s7, s17, 0
	s_add_u32 s8, s16, 0x20000
	s_addc_u32 s9, s17, 0
	s_add_u32 s10, s16, 0x30000
	s_addc_u32 s11, s17, 0
	v_lshlrev_b32_e32 v136, 3, v4
	v_add_u32_e32 v136, 0x20000, v136
	v_lshlrev_b32_e32 v137, 2, v2
	v_add_u32_e32 v137, 0x20800, v137
	global_load_dwordx4 v[204:207], v134, s[16:17]
	global_load_dwordx4 v[208:211], v134, s[6:7]
	global_load_dwordx4 v[212:215], v134, s[8:9]
	global_load_dwordx4 v[216:219], v134, s[10:11]
	global_load_dwordx4 v[222:225], v134, s[16:17] offset:256
	global_load_dwordx4 v[182:185], v134, s[6:7] offset:256
	global_load_dwordx4 v[166:169], v134, s[8:9] offset:256
	global_load_dwordx4 v[170:173], v134, s[10:11] offset:256
	ds_read2_b64 v[142:145], v136 offset0:0 offset1:16
	ds_read2_b64 v[146:149], v136 offset0:32 offset1:48
	ds_read_b128 v[150:153], v137
	ds_read_b128 v[154:157], v137 offset:16
	ds_read_b128 v[158:161], v137 offset:1024
	ds_read_b128 v[162:165], v137 offset:1040
	v_cmp_lt_i32_e32 vcc, v234, v230
	s_nop 1
	v_cndmask_b32_e32 v201, v228, v234, vcc
	v_cmp_lt_i32_e32 vcc, v195, v230
	s_nop 1
	v_cndmask_b32_e32 v203, v228, v195, vcc
	v_lshlrev_b32_e32 v201, 2, v201
	v_lshlrev_b32_e32 v203, 2, v203
	s_waitcnt lgkmcnt(0)
	v_mul_f32_e32 v142, 0x3a000000, v142
	v_mul_f32_e32 v174, v142, v142
	v_fma_f32 v174, v143, s72, -v174
	v_add_f32_e32 v174, 0x3727c5ac, v174
	v_mul_f32_e32 v144, 0x3a000000, v144
	v_mul_f32_e32 v175, v144, v144
	v_fma_f32 v175, v145, s72, -v175
	v_add_f32_e32 v175, 0x3727c5ac, v175
	v_mul_f32_e32 v146, 0x3a000000, v146
	v_mul_f32_e32 v176, v146, v146
	v_fma_f32 v176, v147, s72, -v176
	v_add_f32_e32 v176, 0x3727c5ac, v176
	v_mul_f32_e32 v148, 0x3a000000, v148
	v_mul_f32_e32 v177, v148, v148
	v_fma_f32 v177, v149, s72, -v177
	v_add_f32_e32 v177, 0x3727c5ac, v177
	v_rsq_f32_e32 v143, v174
	v_rsq_f32_e32 v145, v175
	v_rsq_f32_e32 v147, v176
	v_rsq_f32_e32 v149, v177
	s_nop 0
	s_waitcnt vmcnt(7)
	v_lshlrev_b32_e32 v174, 16, v204
	v_and_b32_e32 v175, 0xffff0000, v204
	v_lshlrev_b32_e32 v176, 16, v205
	v_and_b32_e32 v177, 0xffff0000, v205
	v_lshlrev_b32_e32 v178, 16, v206
	v_and_b32_e32 v179, 0xffff0000, v206
	v_lshlrev_b32_e32 v180, 16, v207
	v_and_b32_e32 v181, 0xffff0000, v207
	v_pk_add_f32 v[174:175], v[174:175], v[142:143] op_sel_hi:[1,0] neg_lo:[0,1] neg_hi:[0,1]
	v_pk_add_f32 v[176:177], v[176:177], v[142:143] op_sel_hi:[1,0] neg_lo:[0,1] neg_hi:[0,1]
	v_pk_add_f32 v[178:179], v[178:179], v[142:143] op_sel_hi:[1,0] neg_lo:[0,1] neg_hi:[0,1]
	v_pk_add_f32 v[180:181], v[180:181], v[142:143] op_sel_hi:[1,0] neg_lo:[0,1] neg_hi:[0,1]
	v_pk_mul_f32 v[174:175], v[142:143], v[174:175] op_sel:[1,0] op_sel_hi:[1,1]
	v_pk_mul_f32 v[176:177], v[142:143], v[176:177] op_sel:[1,0] op_sel_hi:[1,1]
	v_pk_mul_f32 v[178:179], v[142:143], v[178:179] op_sel:[1,0] op_sel_hi:[1,1]
	v_pk_mul_f32 v[180:181], v[142:143], v[180:181] op_sel:[1,0] op_sel_hi:[1,1]
	v_pk_fma_f32 v[174:175], v[150:151], v[174:175], v[158:159]
	v_pk_fma_f32 v[176:177], v[152:153], v[176:177], v[160:161]
	v_pk_fma_f32 v[178:179], v[154:155], v[178:179], v[162:163]
	v_pk_fma_f32 v[180:181], v[156:157], v[180:181], v[164:165]
	v_pk_fma_f32 v[126:127], v[174:175], s[76:77], v[126:127] op_sel_hi:[1,0,1]
	v_pk_fma_f32 v[128:129], v[176:177], s[76:77], v[128:129] op_sel_hi:[1,0,1]
	v_pk_fma_f32 v[130:131], v[178:179], s[76:77], v[130:131] op_sel_hi:[1,0,1]
	v_pk_fma_f32 v[132:133], v[180:181], s[76:77], v[132:133] op_sel_hi:[1,0,1]
	v_pk_add_f32 v[174:175], v[126:127], v[130:131]
	v_pk_add_f32 v[176:177], v[128:129], v[132:133]
	v_pk_mul_f32 v[178:179], v[126:127], v[126:127]
	v_pk_mul_f32 v[180:181], v[128:129], v[128:129]
	v_pk_fma_f32 v[178:179], v[130:131], v[130:131], v[178:179]
	v_pk_fma_f32 v[180:181], v[132:133], v[132:133], v[180:181]
	v_pk_add_f32 v[174:175], v[174:175], v[176:177]
	v_pk_add_f32 v[178:179], v[178:179], v[180:181]
	v_cvt_pk_bf16_f32 v204, v126, v127
	v_cvt_pk_bf16_f32 v205, v128, v129
	v_cvt_pk_bf16_f32 v206, v130, v131
	v_cvt_pk_bf16_f32 v207, v132, v133
	v_add_f32_e32 v2, v174, v175
	v_add_f32_e32 v140, v178, v179
	s_waitcnt vmcnt(6)
	v_lshlrev_b32_e32 v174, 16, v208
	v_and_b32_e32 v175, 0xffff0000, v208
	v_lshlrev_b32_e32 v176, 16, v209
	v_and_b32_e32 v177, 0xffff0000, v209
	v_lshlrev_b32_e32 v178, 16, v210
	v_and_b32_e32 v179, 0xffff0000, v210
	v_lshlrev_b32_e32 v180, 16, v211
	v_and_b32_e32 v181, 0xffff0000, v211
	v_pk_add_f32 v[174:175], v[174:175], v[144:145] op_sel_hi:[1,0] neg_lo:[0,1] neg_hi:[0,1]
	v_pk_add_f32 v[176:177], v[176:177], v[144:145] op_sel_hi:[1,0] neg_lo:[0,1] neg_hi:[0,1]
	v_pk_add_f32 v[178:179], v[178:179], v[144:145] op_sel_hi:[1,0] neg_lo:[0,1] neg_hi:[0,1]
	v_pk_add_f32 v[180:181], v[180:181], v[144:145] op_sel_hi:[1,0] neg_lo:[0,1] neg_hi:[0,1]
	v_pk_mul_f32 v[174:175], v[144:145], v[174:175] op_sel:[1,0] op_sel_hi:[1,1]
	v_pk_mul_f32 v[176:177], v[144:145], v[176:177] op_sel:[1,0] op_sel_hi:[1,1]
	v_pk_mul_f32 v[178:179], v[144:145], v[178:179] op_sel:[1,0] op_sel_hi:[1,1]
	v_pk_mul_f32 v[180:181], v[144:145], v[180:181] op_sel:[1,0] op_sel_hi:[1,1]
	v_pk_fma_f32 v[174:175], v[150:151], v[174:175], v[158:159]
	v_pk_fma_f32 v[176:177], v[152:153], v[176:177], v[160:161]
	v_pk_fma_f32 v[178:179], v[154:155], v[178:179], v[162:163]
	v_pk_fma_f32 v[180:181], v[156:157], v[180:181], v[164:165]
	v_pk_fma_f32 v[118:119], v[174:175], s[76:77], v[118:119] op_sel_hi:[1,0,1]
	v_pk_fma_f32 v[120:121], v[176:177], s[76:77], v[120:121] op_sel_hi:[1,0,1]
	v_pk_fma_f32 v[122:123], v[178:179], s[76:77], v[122:123] op_sel_hi:[1,0,1]
	v_pk_fma_f32 v[124:125], v[180:181], s[76:77], v[124:125] op_sel_hi:[1,0,1]
	v_pk_add_f32 v[174:175], v[118:119], v[122:123]
	v_pk_add_f32 v[176:177], v[120:121], v[124:125]
	v_pk_mul_f32 v[178:179], v[118:119], v[118:119]
	v_pk_mul_f32 v[180:181], v[120:121], v[120:121]
	v_pk_fma_f32 v[178:179], v[122:123], v[122:123], v[178:179]
	v_pk_fma_f32 v[180:181], v[124:125], v[124:125], v[180:181]
	v_pk_add_f32 v[174:175], v[174:175], v[176:177]
	v_pk_add_f32 v[178:179], v[178:179], v[180:181]
	v_cvt_pk_bf16_f32 v208, v118, v119
	v_cvt_pk_bf16_f32 v209, v120, v121
	v_cvt_pk_bf16_f32 v210, v122, v123
	v_cvt_pk_bf16_f32 v211, v124, v125
	v_add_f32_e32 v4, v174, v175
	v_add_f32_e32 v186, v178, v179
	s_waitcnt vmcnt(5)
	v_lshlrev_b32_e32 v174, 16, v212
	v_and_b32_e32 v175, 0xffff0000, v212
	v_lshlrev_b32_e32 v176, 16, v213
	v_and_b32_e32 v177, 0xffff0000, v213
	v_lshlrev_b32_e32 v178, 16, v214
	v_and_b32_e32 v179, 0xffff0000, v214
	v_lshlrev_b32_e32 v180, 16, v215
	v_and_b32_e32 v181, 0xffff0000, v215
	v_pk_add_f32 v[174:175], v[174:175], v[146:147] op_sel_hi:[1,0] neg_lo:[0,1] neg_hi:[0,1]
	v_pk_add_f32 v[176:177], v[176:177], v[146:147] op_sel_hi:[1,0] neg_lo:[0,1] neg_hi:[0,1]
	v_pk_add_f32 v[178:179], v[178:179], v[146:147] op_sel_hi:[1,0] neg_lo:[0,1] neg_hi:[0,1]
	v_pk_add_f32 v[180:181], v[180:181], v[146:147] op_sel_hi:[1,0] neg_lo:[0,1] neg_hi:[0,1]
	v_pk_mul_f32 v[174:175], v[146:147], v[174:175] op_sel:[1,0] op_sel_hi:[1,1]
	v_pk_mul_f32 v[176:177], v[146:147], v[176:177] op_sel:[1,0] op_sel_hi:[1,1]
	v_pk_mul_f32 v[178:179], v[146:147], v[178:179] op_sel:[1,0] op_sel_hi:[1,1]
	v_pk_mul_f32 v[180:181], v[146:147], v[180:181] op_sel:[1,0] op_sel_hi:[1,1]
	v_pk_fma_f32 v[174:175], v[150:151], v[174:175], v[158:159]
	v_pk_fma_f32 v[176:177], v[152:153], v[176:177], v[160:161]
	v_pk_fma_f32 v[178:179], v[154:155], v[178:179], v[162:163]
	v_pk_fma_f32 v[180:181], v[156:157], v[180:181], v[164:165]
	v_pk_fma_f32 v[110:111], v[174:175], s[76:77], v[110:111] op_sel_hi:[1,0,1]
	v_pk_fma_f32 v[112:113], v[176:177], s[76:77], v[112:113] op_sel_hi:[1,0,1]
	v_pk_fma_f32 v[114:115], v[178:179], s[76:77], v[114:115] op_sel_hi:[1,0,1]
	v_pk_fma_f32 v[116:117], v[180:181], s[76:77], v[116:117] op_sel_hi:[1,0,1]
	v_pk_add_f32 v[174:175], v[110:111], v[114:115]
	v_pk_add_f32 v[176:177], v[112:113], v[116:117]
	v_pk_mul_f32 v[178:179], v[110:111], v[110:111]
	v_pk_mul_f32 v[180:181], v[112:113], v[112:113]
	v_pk_fma_f32 v[178:179], v[114:115], v[114:115], v[178:179]
	v_pk_fma_f32 v[180:181], v[116:117], v[116:117], v[180:181]
	v_pk_add_f32 v[174:175], v[174:175], v[176:177]
	v_pk_add_f32 v[178:179], v[178:179], v[180:181]
	v_cvt_pk_bf16_f32 v212, v110, v111
	v_cvt_pk_bf16_f32 v213, v112, v113
	v_cvt_pk_bf16_f32 v214, v114, v115
	v_cvt_pk_bf16_f32 v215, v116, v117
	v_add_f32_e32 v5, v174, v175
	v_add_f32_e32 v187, v178, v179
	s_waitcnt vmcnt(4)
	v_lshlrev_b32_e32 v174, 16, v216
	v_and_b32_e32 v175, 0xffff0000, v216
	v_lshlrev_b32_e32 v176, 16, v217
	v_and_b32_e32 v177, 0xffff0000, v217
	v_lshlrev_b32_e32 v178, 16, v218
	v_and_b32_e32 v179, 0xffff0000, v218
	v_lshlrev_b32_e32 v180, 16, v219
	v_and_b32_e32 v181, 0xffff0000, v219
	v_pk_add_f32 v[174:175], v[174:175], v[148:149] op_sel_hi:[1,0] neg_lo:[0,1] neg_hi:[0,1]
	v_pk_add_f32 v[176:177], v[176:177], v[148:149] op_sel_hi:[1,0] neg_lo:[0,1] neg_hi:[0,1]
	v_pk_add_f32 v[178:179], v[178:179], v[148:149] op_sel_hi:[1,0] neg_lo:[0,1] neg_hi:[0,1]
	v_pk_add_f32 v[180:181], v[180:181], v[148:149] op_sel_hi:[1,0] neg_lo:[0,1] neg_hi:[0,1]
	v_pk_mul_f32 v[174:175], v[148:149], v[174:175] op_sel:[1,0] op_sel_hi:[1,1]
	v_pk_mul_f32 v[176:177], v[148:149], v[176:177] op_sel:[1,0] op_sel_hi:[1,1]
	v_pk_mul_f32 v[178:179], v[148:149], v[178:179] op_sel:[1,0] op_sel_hi:[1,1]
	v_pk_mul_f32 v[180:181], v[148:149], v[180:181] op_sel:[1,0] op_sel_hi:[1,1]
	v_pk_fma_f32 v[174:175], v[150:151], v[174:175], v[158:159]
	v_pk_fma_f32 v[176:177], v[152:153], v[176:177], v[160:161]
	v_pk_fma_f32 v[178:179], v[154:155], v[178:179], v[162:163]
	v_pk_fma_f32 v[180:181], v[156:157], v[180:181], v[164:165]
	v_pk_fma_f32 v[102:103], v[174:175], s[76:77], v[102:103] op_sel_hi:[1,0,1]
	v_pk_fma_f32 v[104:105], v[176:177], s[76:77], v[104:105] op_sel_hi:[1,0,1]
	v_pk_fma_f32 v[106:107], v[178:179], s[76:77], v[106:107] op_sel_hi:[1,0,1]
	v_pk_fma_f32 v[108:109], v[180:181], s[76:77], v[108:109] op_sel_hi:[1,0,1]
	v_pk_add_f32 v[174:175], v[102:103], v[106:107]
	v_pk_add_f32 v[176:177], v[104:105], v[108:109]
	v_pk_mul_f32 v[178:179], v[102:103], v[102:103]
	v_pk_mul_f32 v[180:181], v[104:105], v[104:105]
	v_pk_fma_f32 v[178:179], v[106:107], v[106:107], v[178:179]
	v_pk_fma_f32 v[180:181], v[108:109], v[108:109], v[180:181]
	v_pk_add_f32 v[174:175], v[174:175], v[176:177]
	v_pk_add_f32 v[178:179], v[178:179], v[180:181]
	v_cvt_pk_bf16_f32 v216, v102, v103
	v_cvt_pk_bf16_f32 v217, v104, v105
	v_cvt_pk_bf16_f32 v218, v106, v107
	v_cvt_pk_bf16_f32 v219, v108, v109
	v_add_f32_e32 v139, v174, v175
	v_add_f32_e32 v197, v178, v179
	global_load_dwordx4 v[102:105], v135, s[16:17]
	global_load_dwordx4 v[106:109], v135, s[6:7]
	global_load_dwordx4 v[110:113], v135, s[8:9]
	global_load_dwordx4 v[114:117], v135, s[10:11]
	global_load_dwordx4 v[118:121], v135, s[16:17] offset:256
	global_load_dwordx4 v[122:125], v135, s[6:7] offset:256
	global_load_dwordx4 v[126:129], v135, s[8:9] offset:256
	global_load_dwordx4 v[130:133], v135, s[10:11] offset:256
	global_store_dwordx4 v134, v[204:207], s[16:17]
	global_store_dwordx4 v134, v[208:211], s[6:7]
	global_store_dwordx4 v134, v[212:215], s[8:9]
	global_store_dwordx4 v134, v[216:219], s[10:11]
	ds_read_b128 v[150:153], v137 offset:512
	ds_read_b128 v[154:157], v137 offset:528
	ds_read_b128 v[158:161], v137 offset:1536
	ds_read_b128 v[162:165], v137 offset:1552
	s_waitcnt lgkmcnt(0)
	s_waitcnt vmcnt(15)
	v_lshlrev_b32_e32 v174, 16, v222
	v_and_b32_e32 v175, 0xffff0000, v222
	v_lshlrev_b32_e32 v176, 16, v223
	v_and_b32_e32 v177, 0xffff0000, v223
	v_lshlrev_b32_e32 v178, 16, v224
	v_and_b32_e32 v179, 0xffff0000, v224
	v_lshlrev_b32_e32 v180, 16, v225
	v_and_b32_e32 v181, 0xffff0000, v225
	v_pk_add_f32 v[174:175], v[174:175], v[142:143] op_sel_hi:[1,0] neg_lo:[0,1] neg_hi:[0,1]
	v_pk_add_f32 v[176:177], v[176:177], v[142:143] op_sel_hi:[1,0] neg_lo:[0,1] neg_hi:[0,1]
	v_pk_add_f32 v[178:179], v[178:179], v[142:143] op_sel_hi:[1,0] neg_lo:[0,1] neg_hi:[0,1]
	v_pk_add_f32 v[180:181], v[180:181], v[142:143] op_sel_hi:[1,0] neg_lo:[0,1] neg_hi:[0,1]
	v_pk_mul_f32 v[174:175], v[142:143], v[174:175] op_sel:[1,0] op_sel_hi:[1,1]
	v_pk_mul_f32 v[176:177], v[142:143], v[176:177] op_sel:[1,0] op_sel_hi:[1,1]
	v_pk_mul_f32 v[178:179], v[142:143], v[178:179] op_sel:[1,0] op_sel_hi:[1,1]
	v_pk_mul_f32 v[180:181], v[142:143], v[180:181] op_sel:[1,0] op_sel_hi:[1,1]
	v_pk_fma_f32 v[174:175], v[150:151], v[174:175], v[158:159]
	v_pk_fma_f32 v[176:177], v[152:153], v[176:177], v[160:161]
	v_pk_fma_f32 v[178:179], v[154:155], v[178:179], v[162:163]
	v_pk_fma_f32 v[180:181], v[156:157], v[180:181], v[164:165]
	v_pk_fma_f32 v[94:95], v[174:175], s[76:77], v[94:95] op_sel_hi:[1,0,1]
	v_pk_fma_f32 v[96:97], v[176:177], s[76:77], v[96:97] op_sel_hi:[1,0,1]
	v_pk_fma_f32 v[98:99], v[178:179], s[76:77], v[98:99] op_sel_hi:[1,0,1]
	v_pk_fma_f32 v[100:101], v[180:181], s[76:77], v[100:101] op_sel_hi:[1,0,1]
	v_pk_add_f32 v[174:175], v[94:95], v[98:99]
	v_pk_add_f32 v[176:177], v[96:97], v[100:101]
	v_pk_mul_f32 v[178:179], v[94:95], v[94:95]
	v_pk_mul_f32 v[180:181], v[96:97], v[96:97]
	v_pk_fma_f32 v[178:179], v[98:99], v[98:99], v[178:179]
	v_pk_fma_f32 v[180:181], v[100:101], v[100:101], v[180:181]
	v_pk_add_f32 v[174:175], v[174:175], v[176:177]
	v_pk_add_f32 v[178:179], v[178:179], v[180:181]
	v_cvt_pk_bf16_f32 v222, v94, v95
	v_cvt_pk_bf16_f32 v223, v96, v97
	v_cvt_pk_bf16_f32 v224, v98, v99
	v_cvt_pk_bf16_f32 v225, v100, v101
	v_add_f32_e32 v174, v174, v175
	v_add_f32_e32 v178, v178, v179
	v_add_f32_e32 v2, v2, v174
	v_add_f32_e32 v140, v140, v178
	s_waitcnt vmcnt(14)
	v_lshlrev_b32_e32 v174, 16, v182
	v_and_b32_e32 v175, 0xffff0000, v182
	v_lshlrev_b32_e32 v176, 16, v183
	v_and_b32_e32 v177, 0xffff0000, v183
	v_lshlrev_b32_e32 v178, 16, v184
	v_and_b32_e32 v179, 0xffff0000, v184
	v_lshlrev_b32_e32 v180, 16, v185
	v_and_b32_e32 v181, 0xffff0000, v185
	v_pk_add_f32 v[174:175], v[174:175], v[144:145] op_sel_hi:[1,0] neg_lo:[0,1] neg_hi:[0,1]
	v_pk_add_f32 v[176:177], v[176:177], v[144:145] op_sel_hi:[1,0] neg_lo:[0,1] neg_hi:[0,1]
	v_pk_add_f32 v[178:179], v[178:179], v[144:145] op_sel_hi:[1,0] neg_lo:[0,1] neg_hi:[0,1]
	v_pk_add_f32 v[180:181], v[180:181], v[144:145] op_sel_hi:[1,0] neg_lo:[0,1] neg_hi:[0,1]
	v_pk_mul_f32 v[174:175], v[144:145], v[174:175] op_sel:[1,0] op_sel_hi:[1,1]
	v_pk_mul_f32 v[176:177], v[144:145], v[176:177] op_sel:[1,0] op_sel_hi:[1,1]
	v_pk_mul_f32 v[178:179], v[144:145], v[178:179] op_sel:[1,0] op_sel_hi:[1,1]
	v_pk_mul_f32 v[180:181], v[144:145], v[180:181] op_sel:[1,0] op_sel_hi:[1,1]
	v_pk_fma_f32 v[174:175], v[150:151], v[174:175], v[158:159]
	v_pk_fma_f32 v[176:177], v[152:153], v[176:177], v[160:161]
	v_pk_fma_f32 v[178:179], v[154:155], v[178:179], v[162:163]
	v_pk_fma_f32 v[180:181], v[156:157], v[180:181], v[164:165]
	v_pk_fma_f32 v[86:87], v[174:175], s[76:77], v[86:87] op_sel_hi:[1,0,1]
	v_pk_fma_f32 v[88:89], v[176:177], s[76:77], v[88:89] op_sel_hi:[1,0,1]
	v_pk_fma_f32 v[90:91], v[178:179], s[76:77], v[90:91] op_sel_hi:[1,0,1]
	v_pk_fma_f32 v[92:93], v[180:181], s[76:77], v[92:93] op_sel_hi:[1,0,1]
	v_pk_add_f32 v[174:175], v[86:87], v[90:91]
	v_pk_add_f32 v[176:177], v[88:89], v[92:93]
	v_pk_mul_f32 v[178:179], v[86:87], v[86:87]
	v_pk_mul_f32 v[180:181], v[88:89], v[88:89]
	v_pk_fma_f32 v[178:179], v[90:91], v[90:91], v[178:179]
	v_pk_fma_f32 v[180:181], v[92:93], v[92:93], v[180:181]
	v_pk_add_f32 v[174:175], v[174:175], v[176:177]
	v_pk_add_f32 v[178:179], v[178:179], v[180:181]
	v_cvt_pk_bf16_f32 v182, v86, v87
	v_cvt_pk_bf16_f32 v183, v88, v89
	v_cvt_pk_bf16_f32 v184, v90, v91
	v_cvt_pk_bf16_f32 v185, v92, v93
	v_add_f32_e32 v174, v174, v175
	v_add_f32_e32 v178, v178, v179
	v_add_f32_e32 v4, v4, v174
	v_add_f32_e32 v186, v186, v178
	s_waitcnt vmcnt(13)
	v_lshlrev_b32_e32 v174, 16, v166
	v_and_b32_e32 v175, 0xffff0000, v166
	v_lshlrev_b32_e32 v176, 16, v167
	v_and_b32_e32 v177, 0xffff0000, v167
	v_lshlrev_b32_e32 v178, 16, v168
	v_and_b32_e32 v179, 0xffff0000, v168
	v_lshlrev_b32_e32 v180, 16, v169
	v_and_b32_e32 v181, 0xffff0000, v169
	v_pk_add_f32 v[174:175], v[174:175], v[146:147] op_sel_hi:[1,0] neg_lo:[0,1] neg_hi:[0,1]
	v_pk_add_f32 v[176:177], v[176:177], v[146:147] op_sel_hi:[1,0] neg_lo:[0,1] neg_hi:[0,1]
	v_pk_add_f32 v[178:179], v[178:179], v[146:147] op_sel_hi:[1,0] neg_lo:[0,1] neg_hi:[0,1]
	v_pk_add_f32 v[180:181], v[180:181], v[146:147] op_sel_hi:[1,0] neg_lo:[0,1] neg_hi:[0,1]
	v_pk_mul_f32 v[174:175], v[146:147], v[174:175] op_sel:[1,0] op_sel_hi:[1,1]
	v_pk_mul_f32 v[176:177], v[146:147], v[176:177] op_sel:[1,0] op_sel_hi:[1,1]
	v_pk_mul_f32 v[178:179], v[146:147], v[178:179] op_sel:[1,0] op_sel_hi:[1,1]
	v_pk_mul_f32 v[180:181], v[146:147], v[180:181] op_sel:[1,0] op_sel_hi:[1,1]
	v_pk_fma_f32 v[174:175], v[150:151], v[174:175], v[158:159]
	v_pk_fma_f32 v[176:177], v[152:153], v[176:177], v[160:161]
	v_pk_fma_f32 v[178:179], v[154:155], v[178:179], v[162:163]
	v_pk_fma_f32 v[180:181], v[156:157], v[180:181], v[164:165]
	v_pk_fma_f32 v[78:79], v[174:175], s[76:77], v[78:79] op_sel_hi:[1,0,1]
	v_pk_fma_f32 v[80:81], v[176:177], s[76:77], v[80:81] op_sel_hi:[1,0,1]
	v_pk_fma_f32 v[82:83], v[178:179], s[76:77], v[82:83] op_sel_hi:[1,0,1]
	v_pk_fma_f32 v[84:85], v[180:181], s[76:77], v[84:85] op_sel_hi:[1,0,1]
	v_pk_add_f32 v[174:175], v[78:79], v[82:83]
	v_pk_add_f32 v[176:177], v[80:81], v[84:85]
	v_pk_mul_f32 v[178:179], v[78:79], v[78:79]
	v_pk_mul_f32 v[180:181], v[80:81], v[80:81]
	v_pk_fma_f32 v[178:179], v[82:83], v[82:83], v[178:179]
	v_pk_fma_f32 v[180:181], v[84:85], v[84:85], v[180:181]
	v_pk_add_f32 v[174:175], v[174:175], v[176:177]
	v_pk_add_f32 v[178:179], v[178:179], v[180:181]
	v_cvt_pk_bf16_f32 v166, v78, v79
	v_cvt_pk_bf16_f32 v167, v80, v81
	v_cvt_pk_bf16_f32 v168, v82, v83
	v_cvt_pk_bf16_f32 v169, v84, v85
	v_add_f32_e32 v174, v174, v175
	v_add_f32_e32 v178, v178, v179
	v_add_f32_e32 v5, v5, v174
	v_add_f32_e32 v187, v187, v178
	s_waitcnt vmcnt(12)
	v_lshlrev_b32_e32 v174, 16, v170
	v_and_b32_e32 v175, 0xffff0000, v170
	v_lshlrev_b32_e32 v176, 16, v171
	v_and_b32_e32 v177, 0xffff0000, v171
	v_lshlrev_b32_e32 v178, 16, v172
	v_and_b32_e32 v179, 0xffff0000, v172
	v_lshlrev_b32_e32 v180, 16, v173
	v_and_b32_e32 v181, 0xffff0000, v173
	v_pk_add_f32 v[174:175], v[174:175], v[148:149] op_sel_hi:[1,0] neg_lo:[0,1] neg_hi:[0,1]
	v_pk_add_f32 v[176:177], v[176:177], v[148:149] op_sel_hi:[1,0] neg_lo:[0,1] neg_hi:[0,1]
	v_pk_add_f32 v[178:179], v[178:179], v[148:149] op_sel_hi:[1,0] neg_lo:[0,1] neg_hi:[0,1]
	v_pk_add_f32 v[180:181], v[180:181], v[148:149] op_sel_hi:[1,0] neg_lo:[0,1] neg_hi:[0,1]
	v_pk_mul_f32 v[174:175], v[148:149], v[174:175] op_sel:[1,0] op_sel_hi:[1,1]
	v_pk_mul_f32 v[176:177], v[148:149], v[176:177] op_sel:[1,0] op_sel_hi:[1,1]
	v_pk_mul_f32 v[178:179], v[148:149], v[178:179] op_sel:[1,0] op_sel_hi:[1,1]
	v_pk_mul_f32 v[180:181], v[148:149], v[180:181] op_sel:[1,0] op_sel_hi:[1,1]
	v_pk_fma_f32 v[174:175], v[150:151], v[174:175], v[158:159]
	v_pk_fma_f32 v[176:177], v[152:153], v[176:177], v[160:161]
	v_pk_fma_f32 v[178:179], v[154:155], v[178:179], v[162:163]
	v_pk_fma_f32 v[180:181], v[156:157], v[180:181], v[164:165]
	v_pk_fma_f32 v[70:71], v[174:175], s[76:77], v[70:71] op_sel_hi:[1,0,1]
	v_pk_fma_f32 v[72:73], v[176:177], s[76:77], v[72:73] op_sel_hi:[1,0,1]
	v_pk_fma_f32 v[74:75], v[178:179], s[76:77], v[74:75] op_sel_hi:[1,0,1]
	v_pk_fma_f32 v[76:77], v[180:181], s[76:77], v[76:77] op_sel_hi:[1,0,1]
	v_pk_add_f32 v[174:175], v[70:71], v[74:75]
	v_pk_add_f32 v[176:177], v[72:73], v[76:77]
	v_pk_mul_f32 v[178:179], v[70:71], v[70:71]
	v_pk_mul_f32 v[180:181], v[72:73], v[72:73]
	v_pk_fma_f32 v[178:179], v[74:75], v[74:75], v[178:179]
	v_pk_fma_f32 v[180:181], v[76:77], v[76:77], v[180:181]
	v_pk_add_f32 v[174:175], v[174:175], v[176:177]
	v_pk_add_f32 v[178:179], v[178:179], v[180:181]
	v_cvt_pk_bf16_f32 v170, v70, v71
	v_cvt_pk_bf16_f32 v171, v72, v73
	v_cvt_pk_bf16_f32 v172, v74, v75
	v_cvt_pk_bf16_f32 v173, v76, v77
	v_add_f32_e32 v174, v174, v175
	v_add_f32_e32 v178, v178, v179
	v_add_f32_e32 v139, v139, v174
	v_add_f32_e32 v197, v197, v178
	global_store_dwordx4 v134, v[222:225], s[16:17] offset:256
	global_store_dwordx4 v134, v[182:185], s[6:7] offset:256
	global_store_dwordx4 v134, v[166:169], s[8:9] offset:256
	global_store_dwordx4 v134, v[170:173], s[10:11] offset:256
	ds_bpermute_b32 v174, v201, v2
	ds_bpermute_b32 v175, v201, v4
	ds_bpermute_b32 v176, v201, v5
	ds_bpermute_b32 v177, v201, v139
	ds_bpermute_b32 v178, v201, v140
	ds_bpermute_b32 v179, v201, v186
	ds_bpermute_b32 v180, v201, v187
	ds_bpermute_b32 v181, v201, v197
	s_waitcnt lgkmcnt(0)
	v_add_f32_e32 v2, v2, v174
	v_add_f32_e32 v4, v4, v175
	v_add_f32_e32 v5, v5, v176
	v_add_f32_e32 v139, v139, v177
	v_add_f32_e32 v140, v140, v178
	v_add_f32_e32 v186, v186, v179
	v_add_f32_e32 v187, v187, v180
	v_add_f32_e32 v197, v197, v181
	ds_bpermute_b32 v174, v203, v2
	ds_bpermute_b32 v175, v203, v4
	ds_bpermute_b32 v176, v203, v5
	ds_bpermute_b32 v177, v203, v139
	ds_bpermute_b32 v178, v203, v140
	ds_bpermute_b32 v179, v203, v186
	ds_bpermute_b32 v180, v203, v187
	ds_bpermute_b32 v181, v203, v197
	s_waitcnt lgkmcnt(0)
	v_add_f32_e32 v2, v2, v174
	v_add_f32_e32 v4, v4, v175
	v_add_f32_e32 v5, v5, v176
	v_add_f32_e32 v139, v139, v177
	v_add_f32_e32 v140, v140, v178
	v_add_f32_e32 v186, v186, v179
	v_add_f32_e32 v187, v187, v180
	v_add_f32_e32 v197, v197, v181
	v_cmp_eq_u32_e32 vcc, 1, v191
	s_nop 1
	v_cndmask_b32_e32 v2, v2, v4, vcc
	v_cndmask_b32_e32 v140, v140, v186, vcc
	v_cmp_eq_u32_e32 vcc, 2, v191
	s_nop 1
	v_cndmask_b32_e32 v2, v2, v5, vcc
	v_cndmask_b32_e32 v140, v140, v187, vcc
	v_cmp_eq_u32_e32 vcc, 3, v191
	s_nop 1
	v_cndmask_b32_e32 v2, v2, v139, vcc
	v_cndmask_b32_e32 v140, v140, v197, vcc
	global_atomic_add_f32 v138, v2, s[14:15]
	global_atomic_add_f32 v138, v140, s[14:15] offset:4
	ds_read2_b64 v[142:145], v136 offset0:128 offset1:144
	ds_read2_b64 v[146:149], v136 offset0:160 offset1:176
	ds_read_b128 v[150:153], v137
	ds_read_b128 v[154:157], v137 offset:16
	ds_read_b128 v[158:161], v137 offset:1024
	ds_read_b128 v[162:165], v137 offset:1040
	s_waitcnt lgkmcnt(0)
	v_mul_f32_e32 v142, 0x3a000000, v142
	v_mul_f32_e32 v174, v142, v142
	v_fma_f32 v174, v143, s72, -v174
	v_add_f32_e32 v174, 0x3727c5ac, v174
	v_mul_f32_e32 v144, 0x3a000000, v144
	v_mul_f32_e32 v175, v144, v144
	v_fma_f32 v175, v145, s72, -v175
	v_add_f32_e32 v175, 0x3727c5ac, v175
	v_mul_f32_e32 v146, 0x3a000000, v146
	v_mul_f32_e32 v176, v146, v146
	v_fma_f32 v176, v147, s72, -v176
	v_add_f32_e32 v176, 0x3727c5ac, v176
	v_mul_f32_e32 v148, 0x3a000000, v148
	v_mul_f32_e32 v177, v148, v148
	v_fma_f32 v177, v149, s72, -v177
	v_add_f32_e32 v177, 0x3727c5ac, v177
	v_rsq_f32_e32 v143, v174
	v_rsq_f32_e32 v145, v175
	v_rsq_f32_e32 v147, v176
	v_rsq_f32_e32 v149, v177
	s_nop 0
	s_waitcnt vmcnt(17)
	v_lshlrev_b32_e32 v174, 16, v102
	v_and_b32_e32 v175, 0xffff0000, v102
	v_lshlrev_b32_e32 v176, 16, v103
	v_and_b32_e32 v177, 0xffff0000, v103
	v_lshlrev_b32_e32 v178, 16, v104
	v_and_b32_e32 v179, 0xffff0000, v104
	v_lshlrev_b32_e32 v180, 16, v105
	v_and_b32_e32 v181, 0xffff0000, v105
	v_pk_add_f32 v[174:175], v[174:175], v[142:143] op_sel_hi:[1,0] neg_lo:[0,1] neg_hi:[0,1]
	v_pk_add_f32 v[176:177], v[176:177], v[142:143] op_sel_hi:[1,0] neg_lo:[0,1] neg_hi:[0,1]
	v_pk_add_f32 v[178:179], v[178:179], v[142:143] op_sel_hi:[1,0] neg_lo:[0,1] neg_hi:[0,1]
	v_pk_add_f32 v[180:181], v[180:181], v[142:143] op_sel_hi:[1,0] neg_lo:[0,1] neg_hi:[0,1]
	v_pk_mul_f32 v[174:175], v[142:143], v[174:175] op_sel:[1,0] op_sel_hi:[1,1]
	v_pk_mul_f32 v[176:177], v[142:143], v[176:177] op_sel:[1,0] op_sel_hi:[1,1]
	v_pk_mul_f32 v[178:179], v[142:143], v[178:179] op_sel:[1,0] op_sel_hi:[1,1]
	v_pk_mul_f32 v[180:181], v[142:143], v[180:181] op_sel:[1,0] op_sel_hi:[1,1]
	v_pk_fma_f32 v[174:175], v[150:151], v[174:175], v[158:159]
	v_pk_fma_f32 v[176:177], v[152:153], v[176:177], v[160:161]
	v_pk_fma_f32 v[178:179], v[154:155], v[178:179], v[162:163]
	v_pk_fma_f32 v[180:181], v[156:157], v[180:181], v[164:165]
	v_pk_fma_f32 v[46:47], v[174:175], s[76:77], v[46:47] op_sel_hi:[1,0,1]
	v_pk_fma_f32 v[48:49], v[176:177], s[76:77], v[48:49] op_sel_hi:[1,0,1]
	v_pk_fma_f32 v[50:51], v[178:179], s[76:77], v[50:51] op_sel_hi:[1,0,1]
	v_pk_fma_f32 v[52:53], v[180:181], s[76:77], v[52:53] op_sel_hi:[1,0,1]
	v_pk_add_f32 v[174:175], v[46:47], v[50:51]
	v_pk_add_f32 v[176:177], v[48:49], v[52:53]
	v_pk_mul_f32 v[178:179], v[46:47], v[46:47]
	v_pk_mul_f32 v[180:181], v[48:49], v[48:49]
	v_pk_fma_f32 v[178:179], v[50:51], v[50:51], v[178:179]
	v_pk_fma_f32 v[180:181], v[52:53], v[52:53], v[180:181]
	v_pk_add_f32 v[174:175], v[174:175], v[176:177]
	v_pk_add_f32 v[178:179], v[178:179], v[180:181]
	v_cvt_pk_bf16_f32 v102, v46, v47
	v_cvt_pk_bf16_f32 v103, v48, v49
	v_cvt_pk_bf16_f32 v104, v50, v51
	v_cvt_pk_bf16_f32 v105, v52, v53
	v_add_f32_e32 v2, v174, v175
	v_add_f32_e32 v140, v178, v179
	s_waitcnt vmcnt(16)
	v_lshlrev_b32_e32 v174, 16, v106
	v_and_b32_e32 v175, 0xffff0000, v106
	v_lshlrev_b32_e32 v176, 16, v107
	v_and_b32_e32 v177, 0xffff0000, v107
	v_lshlrev_b32_e32 v178, 16, v108
	v_and_b32_e32 v179, 0xffff0000, v108
	v_lshlrev_b32_e32 v180, 16, v109
	v_and_b32_e32 v181, 0xffff0000, v109
	v_pk_add_f32 v[174:175], v[174:175], v[144:145] op_sel_hi:[1,0] neg_lo:[0,1] neg_hi:[0,1]
	v_pk_add_f32 v[176:177], v[176:177], v[144:145] op_sel_hi:[1,0] neg_lo:[0,1] neg_hi:[0,1]
	v_pk_add_f32 v[178:179], v[178:179], v[144:145] op_sel_hi:[1,0] neg_lo:[0,1] neg_hi:[0,1]
	v_pk_add_f32 v[180:181], v[180:181], v[144:145] op_sel_hi:[1,0] neg_lo:[0,1] neg_hi:[0,1]
	v_pk_mul_f32 v[174:175], v[144:145], v[174:175] op_sel:[1,0] op_sel_hi:[1,1]
	v_pk_mul_f32 v[176:177], v[144:145], v[176:177] op_sel:[1,0] op_sel_hi:[1,1]
	v_pk_mul_f32 v[178:179], v[144:145], v[178:179] op_sel:[1,0] op_sel_hi:[1,1]
	v_pk_mul_f32 v[180:181], v[144:145], v[180:181] op_sel:[1,0] op_sel_hi:[1,1]
	v_pk_fma_f32 v[174:175], v[150:151], v[174:175], v[158:159]
	v_pk_fma_f32 v[176:177], v[152:153], v[176:177], v[160:161]
	v_pk_fma_f32 v[178:179], v[154:155], v[178:179], v[162:163]
	v_pk_fma_f32 v[180:181], v[156:157], v[180:181], v[164:165]
	v_pk_fma_f32 v[38:39], v[174:175], s[76:77], v[38:39] op_sel_hi:[1,0,1]
	v_pk_fma_f32 v[40:41], v[176:177], s[76:77], v[40:41] op_sel_hi:[1,0,1]
	v_pk_fma_f32 v[42:43], v[178:179], s[76:77], v[42:43] op_sel_hi:[1,0,1]
	v_pk_fma_f32 v[44:45], v[180:181], s[76:77], v[44:45] op_sel_hi:[1,0,1]
	v_pk_add_f32 v[174:175], v[38:39], v[42:43]
	v_pk_add_f32 v[176:177], v[40:41], v[44:45]
	v_pk_mul_f32 v[178:179], v[38:39], v[38:39]
	v_pk_mul_f32 v[180:181], v[40:41], v[40:41]
	v_pk_fma_f32 v[178:179], v[42:43], v[42:43], v[178:179]
	v_pk_fma_f32 v[180:181], v[44:45], v[44:45], v[180:181]
	v_pk_add_f32 v[174:175], v[174:175], v[176:177]
	v_pk_add_f32 v[178:179], v[178:179], v[180:181]
	v_cvt_pk_bf16_f32 v106, v38, v39
	v_cvt_pk_bf16_f32 v107, v40, v41
	v_cvt_pk_bf16_f32 v108, v42, v43
	v_cvt_pk_bf16_f32 v109, v44, v45
	v_add_f32_e32 v4, v174, v175
	v_add_f32_e32 v186, v178, v179
	s_waitcnt vmcnt(15)
	v_lshlrev_b32_e32 v174, 16, v110
	v_and_b32_e32 v175, 0xffff0000, v110
	v_lshlrev_b32_e32 v176, 16, v111
	v_and_b32_e32 v177, 0xffff0000, v111
	v_lshlrev_b32_e32 v178, 16, v112
	v_and_b32_e32 v179, 0xffff0000, v112
	v_lshlrev_b32_e32 v180, 16, v113
	v_and_b32_e32 v181, 0xffff0000, v113
	v_pk_add_f32 v[174:175], v[174:175], v[146:147] op_sel_hi:[1,0] neg_lo:[0,1] neg_hi:[0,1]
	v_pk_add_f32 v[176:177], v[176:177], v[146:147] op_sel_hi:[1,0] neg_lo:[0,1] neg_hi:[0,1]
	v_pk_add_f32 v[178:179], v[178:179], v[146:147] op_sel_hi:[1,0] neg_lo:[0,1] neg_hi:[0,1]
	v_pk_add_f32 v[180:181], v[180:181], v[146:147] op_sel_hi:[1,0] neg_lo:[0,1] neg_hi:[0,1]
	v_pk_mul_f32 v[174:175], v[146:147], v[174:175] op_sel:[1,0] op_sel_hi:[1,1]
	v_pk_mul_f32 v[176:177], v[146:147], v[176:177] op_sel:[1,0] op_sel_hi:[1,1]
	v_pk_mul_f32 v[178:179], v[146:147], v[178:179] op_sel:[1,0] op_sel_hi:[1,1]
	v_pk_mul_f32 v[180:181], v[146:147], v[180:181] op_sel:[1,0] op_sel_hi:[1,1]
	v_pk_fma_f32 v[174:175], v[150:151], v[174:175], v[158:159]
	v_pk_fma_f32 v[176:177], v[152:153], v[176:177], v[160:161]
	v_pk_fma_f32 v[178:179], v[154:155], v[178:179], v[162:163]
	v_pk_fma_f32 v[180:181], v[156:157], v[180:181], v[164:165]
	v_pk_fma_f32 v[30:31], v[174:175], s[76:77], v[30:31] op_sel_hi:[1,0,1]
	v_pk_fma_f32 v[32:33], v[176:177], s[76:77], v[32:33] op_sel_hi:[1,0,1]
	v_pk_fma_f32 v[34:35], v[178:179], s[76:77], v[34:35] op_sel_hi:[1,0,1]
	v_pk_fma_f32 v[36:37], v[180:181], s[76:77], v[36:37] op_sel_hi:[1,0,1]
	v_pk_add_f32 v[174:175], v[30:31], v[34:35]
	v_pk_add_f32 v[176:177], v[32:33], v[36:37]
	v_pk_mul_f32 v[178:179], v[30:31], v[30:31]
	v_pk_mul_f32 v[180:181], v[32:33], v[32:33]
	v_pk_fma_f32 v[178:179], v[34:35], v[34:35], v[178:179]
	v_pk_fma_f32 v[180:181], v[36:37], v[36:37], v[180:181]
	v_pk_add_f32 v[174:175], v[174:175], v[176:177]
	v_pk_add_f32 v[178:179], v[178:179], v[180:181]
	v_cvt_pk_bf16_f32 v110, v30, v31
	v_cvt_pk_bf16_f32 v111, v32, v33
	v_cvt_pk_bf16_f32 v112, v34, v35
	v_cvt_pk_bf16_f32 v113, v36, v37
	v_add_f32_e32 v5, v174, v175
	v_add_f32_e32 v187, v178, v179
	s_waitcnt vmcnt(14)
	v_lshlrev_b32_e32 v174, 16, v114
	v_and_b32_e32 v175, 0xffff0000, v114
	v_lshlrev_b32_e32 v176, 16, v115
	v_and_b32_e32 v177, 0xffff0000, v115
	v_lshlrev_b32_e32 v178, 16, v116
	v_and_b32_e32 v179, 0xffff0000, v116
	v_lshlrev_b32_e32 v180, 16, v117
	v_and_b32_e32 v181, 0xffff0000, v117
	v_pk_add_f32 v[174:175], v[174:175], v[148:149] op_sel_hi:[1,0] neg_lo:[0,1] neg_hi:[0,1]
	v_pk_add_f32 v[176:177], v[176:177], v[148:149] op_sel_hi:[1,0] neg_lo:[0,1] neg_hi:[0,1]
	v_pk_add_f32 v[178:179], v[178:179], v[148:149] op_sel_hi:[1,0] neg_lo:[0,1] neg_hi:[0,1]
	v_pk_add_f32 v[180:181], v[180:181], v[148:149] op_sel_hi:[1,0] neg_lo:[0,1] neg_hi:[0,1]
	v_pk_mul_f32 v[174:175], v[148:149], v[174:175] op_sel:[1,0] op_sel_hi:[1,1]
	v_pk_mul_f32 v[176:177], v[148:149], v[176:177] op_sel:[1,0] op_sel_hi:[1,1]
	v_pk_mul_f32 v[178:179], v[148:149], v[178:179] op_sel:[1,0] op_sel_hi:[1,1]
	v_pk_mul_f32 v[180:181], v[148:149], v[180:181] op_sel:[1,0] op_sel_hi:[1,1]
	v_pk_fma_f32 v[174:175], v[150:151], v[174:175], v[158:159]
	v_pk_fma_f32 v[176:177], v[152:153], v[176:177], v[160:161]
	v_pk_fma_f32 v[178:179], v[154:155], v[178:179], v[162:163]
	v_pk_fma_f32 v[180:181], v[156:157], v[180:181], v[164:165]
	v_pk_fma_f32 v[22:23], v[174:175], s[76:77], v[22:23] op_sel_hi:[1,0,1]
	v_pk_fma_f32 v[24:25], v[176:177], s[76:77], v[24:25] op_sel_hi:[1,0,1]
	v_pk_fma_f32 v[26:27], v[178:179], s[76:77], v[26:27] op_sel_hi:[1,0,1]
	v_pk_fma_f32 v[28:29], v[180:181], s[76:77], v[28:29] op_sel_hi:[1,0,1]
	v_pk_add_f32 v[174:175], v[22:23], v[26:27]
	v_pk_add_f32 v[176:177], v[24:25], v[28:29]
	v_pk_mul_f32 v[178:179], v[22:23], v[22:23]
	v_pk_mul_f32 v[180:181], v[24:25], v[24:25]
	v_pk_fma_f32 v[178:179], v[26:27], v[26:27], v[178:179]
	v_pk_fma_f32 v[180:181], v[28:29], v[28:29], v[180:181]
	v_pk_add_f32 v[174:175], v[174:175], v[176:177]
	v_pk_add_f32 v[178:179], v[178:179], v[180:181]
	v_cvt_pk_bf16_f32 v114, v22, v23
	v_cvt_pk_bf16_f32 v115, v24, v25
	v_cvt_pk_bf16_f32 v116, v26, v27
	v_cvt_pk_bf16_f32 v117, v28, v29
	v_add_f32_e32 v139, v174, v175
	v_add_f32_e32 v197, v178, v179
	global_store_dwordx4 v135, v[102:105], s[16:17]
	global_store_dwordx4 v135, v[106:109], s[6:7]
	global_store_dwordx4 v135, v[110:113], s[8:9]
	global_store_dwordx4 v135, v[114:117], s[10:11]
	ds_read_b128 v[150:153], v137 offset:512
	ds_read_b128 v[154:157], v137 offset:528
	ds_read_b128 v[158:161], v137 offset:1536
	ds_read_b128 v[162:165], v137 offset:1552
	s_waitcnt lgkmcnt(0)
	s_waitcnt vmcnt(17)
	v_lshlrev_b32_e32 v174, 16, v118
	v_and_b32_e32 v175, 0xffff0000, v118
	v_lshlrev_b32_e32 v176, 16, v119
	v_and_b32_e32 v177, 0xffff0000, v119
	v_lshlrev_b32_e32 v178, 16, v120
	v_and_b32_e32 v179, 0xffff0000, v120
	v_lshlrev_b32_e32 v180, 16, v121
	v_and_b32_e32 v181, 0xffff0000, v121
	v_pk_add_f32 v[174:175], v[174:175], v[142:143] op_sel_hi:[1,0] neg_lo:[0,1] neg_hi:[0,1]
	v_pk_add_f32 v[176:177], v[176:177], v[142:143] op_sel_hi:[1,0] neg_lo:[0,1] neg_hi:[0,1]
	v_pk_add_f32 v[178:179], v[178:179], v[142:143] op_sel_hi:[1,0] neg_lo:[0,1] neg_hi:[0,1]
	v_pk_add_f32 v[180:181], v[180:181], v[142:143] op_sel_hi:[1,0] neg_lo:[0,1] neg_hi:[0,1]
	v_pk_mul_f32 v[174:175], v[142:143], v[174:175] op_sel:[1,0] op_sel_hi:[1,1]
	v_pk_mul_f32 v[176:177], v[142:143], v[176:177] op_sel:[1,0] op_sel_hi:[1,1]
	v_pk_mul_f32 v[178:179], v[142:143], v[178:179] op_sel:[1,0] op_sel_hi:[1,1]
	v_pk_mul_f32 v[180:181], v[142:143], v[180:181] op_sel:[1,0] op_sel_hi:[1,1]
	v_pk_fma_f32 v[174:175], v[150:151], v[174:175], v[158:159]
	v_pk_fma_f32 v[176:177], v[152:153], v[176:177], v[160:161]
	v_pk_fma_f32 v[178:179], v[154:155], v[178:179], v[162:163]
	v_pk_fma_f32 v[180:181], v[156:157], v[180:181], v[164:165]
	v_pk_fma_f32 v[14:15], v[174:175], s[76:77], v[14:15] op_sel_hi:[1,0,1]
	v_pk_fma_f32 v[16:17], v[176:177], s[76:77], v[16:17] op_sel_hi:[1,0,1]
	v_pk_fma_f32 v[18:19], v[178:179], s[76:77], v[18:19] op_sel_hi:[1,0,1]
	v_pk_fma_f32 v[20:21], v[180:181], s[76:77], v[20:21] op_sel_hi:[1,0,1]
	v_pk_add_f32 v[174:175], v[14:15], v[18:19]
	v_pk_add_f32 v[176:177], v[16:17], v[20:21]
	v_pk_mul_f32 v[178:179], v[14:15], v[14:15]
	v_pk_mul_f32 v[180:181], v[16:17], v[16:17]
	v_pk_fma_f32 v[178:179], v[18:19], v[18:19], v[178:179]
	v_pk_fma_f32 v[180:181], v[20:21], v[20:21], v[180:181]
	v_pk_add_f32 v[174:175], v[174:175], v[176:177]
	v_pk_add_f32 v[178:179], v[178:179], v[180:181]
	v_cvt_pk_bf16_f32 v118, v14, v15
	v_cvt_pk_bf16_f32 v119, v16, v17
	v_cvt_pk_bf16_f32 v120, v18, v19
	v_cvt_pk_bf16_f32 v121, v20, v21
	v_add_f32_e32 v174, v174, v175
	v_add_f32_e32 v178, v178, v179
	v_add_f32_e32 v2, v2, v174
	v_add_f32_e32 v140, v140, v178
	s_waitcnt vmcnt(16)
	v_lshlrev_b32_e32 v174, 16, v122
	v_and_b32_e32 v175, 0xffff0000, v122
	v_lshlrev_b32_e32 v176, 16, v123
	v_and_b32_e32 v177, 0xffff0000, v123
	v_lshlrev_b32_e32 v178, 16, v124
	v_and_b32_e32 v179, 0xffff0000, v124
	v_lshlrev_b32_e32 v180, 16, v125
	v_and_b32_e32 v181, 0xffff0000, v125
	v_pk_add_f32 v[174:175], v[174:175], v[144:145] op_sel_hi:[1,0] neg_lo:[0,1] neg_hi:[0,1]
	v_pk_add_f32 v[176:177], v[176:177], v[144:145] op_sel_hi:[1,0] neg_lo:[0,1] neg_hi:[0,1]
	v_pk_add_f32 v[178:179], v[178:179], v[144:145] op_sel_hi:[1,0] neg_lo:[0,1] neg_hi:[0,1]
	v_pk_add_f32 v[180:181], v[180:181], v[144:145] op_sel_hi:[1,0] neg_lo:[0,1] neg_hi:[0,1]
	v_pk_mul_f32 v[174:175], v[144:145], v[174:175] op_sel:[1,0] op_sel_hi:[1,1]
	v_pk_mul_f32 v[176:177], v[144:145], v[176:177] op_sel:[1,0] op_sel_hi:[1,1]
	v_pk_mul_f32 v[178:179], v[144:145], v[178:179] op_sel:[1,0] op_sel_hi:[1,1]
	v_pk_mul_f32 v[180:181], v[144:145], v[180:181] op_sel:[1,0] op_sel_hi:[1,1]
	v_pk_fma_f32 v[174:175], v[150:151], v[174:175], v[158:159]
	v_pk_fma_f32 v[176:177], v[152:153], v[176:177], v[160:161]
	v_pk_fma_f32 v[178:179], v[154:155], v[178:179], v[162:163]
	v_pk_fma_f32 v[180:181], v[156:157], v[180:181], v[164:165]
	v_pk_fma_f32 v[6:7], v[174:175], s[76:77], v[6:7] op_sel_hi:[1,0,1]
	v_pk_fma_f32 v[8:9], v[176:177], s[76:77], v[8:9] op_sel_hi:[1,0,1]
	v_pk_fma_f32 v[10:11], v[178:179], s[76:77], v[10:11] op_sel_hi:[1,0,1]
	v_pk_fma_f32 v[12:13], v[180:181], s[76:77], v[12:13] op_sel_hi:[1,0,1]
	v_pk_add_f32 v[174:175], v[6:7], v[10:11]
	v_pk_add_f32 v[176:177], v[8:9], v[12:13]
	v_pk_mul_f32 v[178:179], v[6:7], v[6:7]
	v_pk_mul_f32 v[180:181], v[8:9], v[8:9]
	v_pk_fma_f32 v[178:179], v[10:11], v[10:11], v[178:179]
	v_pk_fma_f32 v[180:181], v[12:13], v[12:13], v[180:181]
	v_pk_add_f32 v[174:175], v[174:175], v[176:177]
	v_pk_add_f32 v[178:179], v[178:179], v[180:181]
	v_cvt_pk_bf16_f32 v122, v6, v7
	v_cvt_pk_bf16_f32 v123, v8, v9
	v_cvt_pk_bf16_f32 v124, v10, v11
	v_cvt_pk_bf16_f32 v125, v12, v13
	v_add_f32_e32 v174, v174, v175
	v_add_f32_e32 v178, v178, v179
	v_add_f32_e32 v4, v4, v174
	v_add_f32_e32 v186, v186, v178
	s_waitcnt vmcnt(15)
	v_lshlrev_b32_e32 v174, 16, v126
	v_and_b32_e32 v175, 0xffff0000, v126
	v_lshlrev_b32_e32 v176, 16, v127
	v_and_b32_e32 v177, 0xffff0000, v127
	v_lshlrev_b32_e32 v178, 16, v128
	v_and_b32_e32 v179, 0xffff0000, v128
	v_lshlrev_b32_e32 v180, 16, v129
	v_and_b32_e32 v181, 0xffff0000, v129
	v_pk_add_f32 v[174:175], v[174:175], v[146:147] op_sel_hi:[1,0] neg_lo:[0,1] neg_hi:[0,1]
	v_pk_add_f32 v[176:177], v[176:177], v[146:147] op_sel_hi:[1,0] neg_lo:[0,1] neg_hi:[0,1]
	v_pk_add_f32 v[178:179], v[178:179], v[146:147] op_sel_hi:[1,0] neg_lo:[0,1] neg_hi:[0,1]
	v_pk_add_f32 v[180:181], v[180:181], v[146:147] op_sel_hi:[1,0] neg_lo:[0,1] neg_hi:[0,1]
	v_pk_mul_f32 v[174:175], v[146:147], v[174:175] op_sel:[1,0] op_sel_hi:[1,1]
	v_pk_mul_f32 v[176:177], v[146:147], v[176:177] op_sel:[1,0] op_sel_hi:[1,1]
	v_pk_mul_f32 v[178:179], v[146:147], v[178:179] op_sel:[1,0] op_sel_hi:[1,1]
	v_pk_mul_f32 v[180:181], v[146:147], v[180:181] op_sel:[1,0] op_sel_hi:[1,1]
	v_pk_fma_f32 v[174:175], v[150:151], v[174:175], v[158:159]
	v_pk_fma_f32 v[176:177], v[152:153], v[176:177], v[160:161]
	v_pk_fma_f32 v[178:179], v[154:155], v[178:179], v[162:163]
	v_pk_fma_f32 v[180:181], v[156:157], v[180:181], v[164:165]
	v_pk_fma_f32 v[54:55], v[174:175], s[76:77], v[54:55] op_sel_hi:[1,0,1]
	v_pk_fma_f32 v[56:57], v[176:177], s[76:77], v[56:57] op_sel_hi:[1,0,1]
	v_pk_fma_f32 v[62:63], v[178:179], s[76:77], v[62:63] op_sel_hi:[1,0,1]
	v_pk_fma_f32 v[64:65], v[180:181], s[76:77], v[64:65] op_sel_hi:[1,0,1]
	v_pk_add_f32 v[174:175], v[54:55], v[62:63]
	v_pk_add_f32 v[176:177], v[56:57], v[64:65]
	v_pk_mul_f32 v[178:179], v[54:55], v[54:55]
	v_pk_mul_f32 v[180:181], v[56:57], v[56:57]
	v_pk_fma_f32 v[178:179], v[62:63], v[62:63], v[178:179]
	v_pk_fma_f32 v[180:181], v[64:65], v[64:65], v[180:181]
	v_pk_add_f32 v[174:175], v[174:175], v[176:177]
	v_pk_add_f32 v[178:179], v[178:179], v[180:181]
	v_cvt_pk_bf16_f32 v126, v54, v55
	v_cvt_pk_bf16_f32 v127, v56, v57
	v_cvt_pk_bf16_f32 v128, v62, v63
	v_cvt_pk_bf16_f32 v129, v64, v65
	v_add_f32_e32 v174, v174, v175
	v_add_f32_e32 v178, v178, v179
	v_add_f32_e32 v5, v5, v174
	v_add_f32_e32 v187, v187, v178
	s_waitcnt vmcnt(14)
	v_lshlrev_b32_e32 v174, 16, v130
	v_and_b32_e32 v175, 0xffff0000, v130
	v_lshlrev_b32_e32 v176, 16, v131
	v_and_b32_e32 v177, 0xffff0000, v131
	v_lshlrev_b32_e32 v178, 16, v132
	v_and_b32_e32 v179, 0xffff0000, v132
	v_lshlrev_b32_e32 v180, 16, v133
	v_and_b32_e32 v181, 0xffff0000, v133
	v_pk_add_f32 v[174:175], v[174:175], v[148:149] op_sel_hi:[1,0] neg_lo:[0,1] neg_hi:[0,1]
	v_pk_add_f32 v[176:177], v[176:177], v[148:149] op_sel_hi:[1,0] neg_lo:[0,1] neg_hi:[0,1]
	v_pk_add_f32 v[178:179], v[178:179], v[148:149] op_sel_hi:[1,0] neg_lo:[0,1] neg_hi:[0,1]
	v_pk_add_f32 v[180:181], v[180:181], v[148:149] op_sel_hi:[1,0] neg_lo:[0,1] neg_hi:[0,1]
	v_pk_mul_f32 v[174:175], v[148:149], v[174:175] op_sel:[1,0] op_sel_hi:[1,1]
	v_pk_mul_f32 v[176:177], v[148:149], v[176:177] op_sel:[1,0] op_sel_hi:[1,1]
	v_pk_mul_f32 v[178:179], v[148:149], v[178:179] op_sel:[1,0] op_sel_hi:[1,1]
	v_pk_mul_f32 v[180:181], v[148:149], v[180:181] op_sel:[1,0] op_sel_hi:[1,1]
	v_pk_fma_f32 v[174:175], v[150:151], v[174:175], v[158:159]
	v_pk_fma_f32 v[176:177], v[152:153], v[176:177], v[160:161]
	v_pk_fma_f32 v[178:179], v[154:155], v[178:179], v[162:163]
	v_pk_fma_f32 v[180:181], v[156:157], v[180:181], v[164:165]
	v_pk_fma_f32 v[58:59], v[174:175], s[76:77], v[58:59] op_sel_hi:[1,0,1]
	v_pk_fma_f32 v[60:61], v[176:177], s[76:77], v[60:61] op_sel_hi:[1,0,1]
	v_pk_fma_f32 v[66:67], v[178:179], s[76:77], v[66:67] op_sel_hi:[1,0,1]
	v_pk_fma_f32 v[68:69], v[180:181], s[76:77], v[68:69] op_sel_hi:[1,0,1]
	v_pk_add_f32 v[174:175], v[58:59], v[66:67]
	v_pk_add_f32 v[176:177], v[60:61], v[68:69]
	v_pk_mul_f32 v[178:179], v[58:59], v[58:59]
	v_pk_mul_f32 v[180:181], v[60:61], v[60:61]
	v_pk_fma_f32 v[178:179], v[66:67], v[66:67], v[178:179]
	v_pk_fma_f32 v[180:181], v[68:69], v[68:69], v[180:181]
	v_pk_add_f32 v[174:175], v[174:175], v[176:177]
	v_pk_add_f32 v[178:179], v[178:179], v[180:181]
	v_cvt_pk_bf16_f32 v130, v58, v59
	v_cvt_pk_bf16_f32 v131, v60, v61
	v_cvt_pk_bf16_f32 v132, v66, v67
	v_cvt_pk_bf16_f32 v133, v68, v69
	v_add_f32_e32 v174, v174, v175
	v_add_f32_e32 v178, v178, v179
	v_add_f32_e32 v139, v139, v174
	v_add_f32_e32 v197, v197, v178
	global_store_dwordx4 v135, v[118:121], s[16:17] offset:256
	global_store_dwordx4 v135, v[122:125], s[6:7] offset:256
	global_store_dwordx4 v135, v[126:129], s[8:9] offset:256
	global_store_dwordx4 v135, v[130:133], s[10:11] offset:256
	ds_bpermute_b32 v174, v201, v2
	ds_bpermute_b32 v175, v201, v4
	ds_bpermute_b32 v176, v201, v5
	ds_bpermute_b32 v177, v201, v139
	ds_bpermute_b32 v178, v201, v140
	ds_bpermute_b32 v179, v201, v186
	ds_bpermute_b32 v180, v201, v187
	ds_bpermute_b32 v181, v201, v197
	s_waitcnt lgkmcnt(0)
	v_add_f32_e32 v2, v2, v174
	v_add_f32_e32 v4, v4, v175
	v_add_f32_e32 v5, v5, v176
	v_add_f32_e32 v139, v139, v177
	v_add_f32_e32 v140, v140, v178
	v_add_f32_e32 v186, v186, v179
	v_add_f32_e32 v187, v187, v180
	v_add_f32_e32 v197, v197, v181
	ds_bpermute_b32 v174, v203, v2
	ds_bpermute_b32 v175, v203, v4
	ds_bpermute_b32 v176, v203, v5
	ds_bpermute_b32 v177, v203, v139
	ds_bpermute_b32 v178, v203, v140
	ds_bpermute_b32 v179, v203, v186
	ds_bpermute_b32 v180, v203, v187
	ds_bpermute_b32 v181, v203, v197
	s_waitcnt lgkmcnt(0)
	v_add_f32_e32 v2, v2, v174
	v_add_f32_e32 v4, v4, v175
	v_add_f32_e32 v5, v5, v176
	v_add_f32_e32 v139, v139, v177
	v_add_f32_e32 v140, v140, v178
	v_add_f32_e32 v186, v186, v179
	v_add_f32_e32 v187, v187, v180
	v_add_f32_e32 v197, v197, v181
	v_cmp_eq_u32_e32 vcc, 1, v191
	s_nop 1
	v_cndmask_b32_e32 v2, v2, v4, vcc
	v_cndmask_b32_e32 v140, v140, v186, vcc
	v_cmp_eq_u32_e32 vcc, 2, v191
	s_nop 1
	v_cndmask_b32_e32 v2, v2, v5, vcc
	v_cndmask_b32_e32 v140, v140, v187, vcc
	v_cmp_eq_u32_e32 vcc, 3, v191
	s_nop 1
	v_cndmask_b32_e32 v2, v2, v139, vcc
	v_cndmask_b32_e32 v140, v140, v197, vcc
	global_atomic_add_f32 v138, v2, s[14:15] offset:1024
	global_atomic_add_f32 v138, v140, s[14:15] offset:1028
	s_branch .LBB0_1171
